# dwconv LayerNorm reductions: ds_bpermute butterflies replaced by DPP row/bcast reductions
# speedup vs baseline: 1.0047x; 1.0037x over previous
.LBB0_501:
	s_cmpk_lt_i32 s94, 0x400
	s_cselect_b32 s89, 0, 0x4000
	s_cselect_b32 s88, s86, 0x4100
	s_add_i32 s3, s2, -15
	s_cmp_ge_i32 s3, s89
	s_cselect_b64 s[0:1], -1, 0
	s_cmp_lt_i32 s3, s88
	s_cselect_b64 s[4:5], -1, 0
	s_and_b64 s[0:1], s[0:1], s[4:5]
	s_and_b64 s[4:5], s[0:1], exec
	s_cselect_b32 s4, s3, s2
	s_ashr_i32 s5, s4, 31
	s_lshl_b64 s[4:5], s[4:5], 11
	s_add_i32 s3, s2, -14
	s_cmp_ge_i32 s3, s89
	v_lshl_add_u64 v[18:19], v[114:115], 0, s[4:5]
	s_cselect_b64 s[4:5], -1, 0
	s_cmp_lt_i32 s3, s88
	s_cselect_b64 s[6:7], -1, 0
	s_and_b64 s[6:7], s[4:5], s[6:7]
	s_and_b64 s[4:5], s[6:7], exec
	s_cselect_b32 s4, s3, s2
	s_ashr_i32 s5, s4, 31
	s_lshl_b64 s[4:5], s[4:5], 11
	s_add_i32 s3, s2, -13
	s_cmp_ge_i32 s3, s89
	global_load_dword v0, v[18:19], off
	v_lshl_add_u64 v[18:19], v[114:115], 0, s[4:5]
	s_cselect_b64 s[4:5], -1, 0
	s_cmp_lt_i32 s3, s88
	s_cselect_b64 s[8:9], -1, 0
	s_and_b64 s[12:13], s[4:5], s[8:9]
	s_and_b64 s[4:5], s[12:13], exec
	s_cselect_b32 s4, s3, s2
	s_ashr_i32 s5, s4, 31
	s_lshl_b64 s[4:5], s[4:5], 11
	s_add_i32 s3, s2, -12
	s_cmp_ge_i32 s3, s89
	v_lshl_add_u64 v[20:21], v[114:115], 0, s[4:5]
	s_cselect_b64 s[4:5], -1, 0
	s_cmp_lt_i32 s3, s88
	s_cselect_b64 s[8:9], -1, 0
	s_and_b64 s[30:31], s[4:5], s[8:9]
	s_and_b64 s[4:5], s[30:31], exec
	s_cselect_b32 s4, s3, s2
	s_ashr_i32 s5, s4, 31
	s_lshl_b64 s[4:5], s[4:5], 11
	s_add_i32 s3, s2, -11
	s_cmp_ge_i32 s3, s89
	v_lshl_add_u64 v[22:23], v[114:115], 0, s[4:5]
	s_cselect_b64 s[4:5], -1, 0
	s_cmp_lt_i32 s3, s88
	s_cselect_b64 s[8:9], -1, 0
	s_and_b64 s[36:37], s[4:5], s[8:9]
	s_and_b64 s[4:5], s[36:37], exec
	s_cselect_b32 s4, s3, s2
	s_ashr_i32 s5, s4, 31
	s_lshl_b64 s[4:5], s[4:5], 11
	s_add_i32 s3, s2, -10
	s_cmp_ge_i32 s3, s89
	global_load_dword v18, v[18:19], off
	s_mov_b32 s96, s70
	global_load_dword v21, v[20:21], off
	s_mov_b32 s97, s84
	global_load_dword v29, v[22:23], off
	v_lshl_add_u64 v[22:23], v[114:115], 0, s[4:5]
	s_cselect_b64 s[4:5], -1, 0
	s_cmp_lt_i32 s3, s88
	s_cselect_b64 s[8:9], -1, 0
	s_and_b64 s[50:51], s[4:5], s[8:9]
	s_and_b64 s[4:5], s[50:51], exec
	s_cselect_b32 s4, s3, s2
	s_ashr_i32 s5, s4, 31
	s_lshl_b64 s[4:5], s[4:5], 11
	s_add_i32 s3, s2, -9
	s_cmp_ge_i32 s3, s89
	global_load_dword v32, v[22:23], off
	v_lshl_add_u64 v[22:23], v[114:115], 0, s[4:5]
	s_cselect_b64 s[4:5], -1, 0
	s_cmp_lt_i32 s3, s88
	s_cselect_b64 s[8:9], -1, 0
	s_and_b64 s[58:59], s[4:5], s[8:9]
	s_and_b64 s[4:5], s[58:59], exec
	s_cselect_b32 s4, s3, s2
	s_ashr_i32 s5, s4, 31
	s_lshl_b64 s[4:5], s[4:5], 11
	s_add_i32 s3, s2, -8
	s_cmp_gt_i32 s2, s89
	global_load_dword v38, v[22:23], off
	v_lshl_add_u64 v[22:23], v[114:115], 0, s[4:5]
	s_cselect_b64 s[4:5], -1, 0
	s_cmp_le_i32 s2, s88
	s_cselect_b64 s[8:9], -1, 0
	s_and_b64 vcc, s[4:5], s[8:9]
	s_and_b64 s[4:5], vcc, exec
	s_cselect_b32 s4, s3, s2
	s_ashr_i32 s5, s4, 31
	s_lshl_b64 s[4:5], s[4:5], 11
	s_add_i32 s3, s2, -7
	s_cmp_ge_i32 s3, s89
	global_load_dword v43, v[22:23], off
	v_lshl_add_u64 v[22:23], v[114:115], 0, s[4:5]
	s_cselect_b64 s[4:5], -1, 0
	s_cmp_lt_i32 s3, s88
	s_cselect_b64 s[8:9], -1, 0
	s_and_b64 s[70:71], s[4:5], s[8:9]
	s_and_b64 s[4:5], s[70:71], exec
	s_cselect_b32 s4, s3, s2
	s_ashr_i32 s5, s4, 31
	s_lshl_b64 s[4:5], s[4:5], 11
	s_add_i32 s3, s2, -6
	s_cmp_ge_i32 s3, s89
	global_load_dword v119, v[22:23], off
	v_lshl_add_u64 v[22:23], v[114:115], 0, s[4:5]
	s_cselect_b64 s[4:5], -1, 0
	s_cmp_lt_i32 s3, s88
	s_cselect_b64 s[8:9], -1, 0
	s_and_b64 s[76:77], s[4:5], s[8:9]
	s_and_b64 s[4:5], s[76:77], exec
	s_cselect_b32 s4, s3, s2
	s_ashr_i32 s5, s4, 31
	s_lshl_b64 s[4:5], s[4:5], 11
	s_add_i32 s3, s2, -5
	s_cmp_ge_i32 s3, s89
	global_load_dword v134, v[22:23], off
	v_lshl_add_u64 v[22:23], v[114:115], 0, s[4:5]
	s_cselect_b64 s[4:5], -1, 0
	s_cmp_lt_i32 s3, s88
	s_cselect_b64 s[8:9], -1, 0
	s_and_b64 s[78:79], s[4:5], s[8:9]
	s_and_b64 s[4:5], s[78:79], exec
	s_cselect_b32 s4, s3, s2
	s_ashr_i32 s5, s4, 31
	s_lshl_b64 s[4:5], s[4:5], 11
	s_add_i32 s3, s2, -4
	global_load_dword v137, v[22:23], off
	v_lshl_add_u64 v[22:23], v[114:115], 0, s[4:5]
	s_and_b64 s[4:5], vcc, exec
	s_cselect_b32 s4, s3, s2
	s_ashr_i32 s5, s4, 31
	s_lshl_b64 s[4:5], s[4:5], 11
	s_add_i32 s3, s2, -3
	s_cmp_ge_i32 s3, s89
	global_load_dword v138, v[22:23], off
	v_lshl_add_u64 v[22:23], v[114:115], 0, s[4:5]
	s_cselect_b64 s[4:5], -1, 0
	s_cmp_lt_i32 s3, s88
	s_cselect_b64 s[8:9], -1, 0
	s_and_b64 s[74:75], s[4:5], s[8:9]
	s_and_b64 s[4:5], s[74:75], exec
	s_cselect_b32 s4, s3, s2
	s_ashr_i32 s5, s4, 31
	s_lshl_b64 s[4:5], s[4:5], 11
	s_add_i32 s3, s2, -2
	global_load_dword v135, v[22:23], off
	v_lshl_add_u64 v[22:23], v[114:115], 0, s[4:5]
	s_and_b64 s[4:5], vcc, exec
	s_cselect_b32 s4, s3, s2
	s_ashr_i32 s5, s4, 31
	s_lshl_b64 s[4:5], s[4:5], 11
	s_cmp_lg_u64 vcc, 0
	global_load_dword v136, v[22:23], off
	v_lshl_add_u64 v[22:23], v[114:115], 0, s[4:5]
	s_subb_u32 s4, s2, 0
	s_ashr_i32 s5, s4, 31
	s_lshl_b64 s[4:5], s[4:5], 11
	s_ashr_i32 s3, s2, 31
	global_load_dword v121, v[22:23], off
	v_lshl_add_u64 v[22:23], v[114:115], 0, s[4:5]
	s_lshl_b64 s[4:5], s[2:3], 11
	s_add_i32 s3, s2, 1
	s_cmp_ge_i32 s3, s89
	global_load_dword v49, v[22:23], off
	v_lshl_add_u64 v[22:23], v[114:115], 0, s[4:5]
	s_cselect_b64 s[4:5], -1, 0
	s_cmp_lt_i32 s3, s88
	s_cselect_b64 s[8:9], -1, 0
	s_and_b64 s[64:65], s[4:5], s[8:9]
	s_and_b64 s[4:5], s[64:65], exec
	s_cselect_b32 s4, s3, s2
	s_ashr_i32 s5, s4, 31
	s_lshl_b64 s[4:5], s[4:5], 11
	s_add_i32 s3, s2, 2
	s_cmp_ge_i32 s3, s89
	global_load_dword v47, v[22:23], off
	v_lshl_add_u64 v[22:23], v[114:115], 0, s[4:5]
	s_cselect_b64 s[4:5], -1, 0
	s_cmp_lt_i32 s3, s88
	s_cselect_b64 s[8:9], -1, 0
	s_and_b64 s[62:63], s[4:5], s[8:9]
	s_and_b64 s[4:5], s[62:63], exec
	s_cselect_b32 s4, s3, s2
	s_ashr_i32 s5, s4, 31
	s_lshl_b64 s[4:5], s[4:5], 11
	s_add_i32 s3, s2, 3
	s_cmp_ge_i32 s3, s89
	global_load_dword v48, v[22:23], off
	v_lshl_add_u64 v[22:23], v[114:115], 0, s[4:5]
	s_cselect_b64 s[4:5], -1, 0
	s_cmp_lt_i32 s3, s88
	s_cselect_b64 s[8:9], -1, 0
	s_and_b64 s[60:61], s[4:5], s[8:9]
	s_and_b64 s[4:5], s[60:61], exec
	s_cselect_b32 s4, s3, s2
	s_ashr_i32 s5, s4, 31
	s_lshl_b64 s[4:5], s[4:5], 11
	s_add_i32 s3, s2, 4
	s_cmp_ge_i32 s3, s89
	global_load_dword v46, v[22:23], off
	v_lshl_add_u64 v[22:23], v[114:115], 0, s[4:5]
	s_cselect_b64 s[4:5], -1, 0
	s_cmp_lt_i32 s3, s88
	s_cselect_b64 s[8:9], -1, 0
	s_and_b64 s[56:57], s[4:5], s[8:9]
	s_and_b64 s[4:5], s[56:57], exec
	s_cselect_b32 s4, s3, s2
	s_ashr_i32 s5, s4, 31
	s_lshl_b64 s[4:5], s[4:5], 11
	s_add_i32 s3, s2, 5
	s_cmp_ge_i32 s3, s89
	global_load_dword v44, v[22:23], off
	v_lshl_add_u64 v[22:23], v[114:115], 0, s[4:5]
	s_cselect_b64 s[4:5], -1, 0
	s_cmp_lt_i32 s3, s88
	s_cselect_b64 s[8:9], -1, 0
	s_and_b64 s[52:53], s[4:5], s[8:9]
	s_and_b64 s[4:5], s[52:53], exec
	s_cselect_b32 s4, s3, s2
	s_ashr_i32 s5, s4, 31
	s_lshl_b64 s[4:5], s[4:5], 11
	s_add_i32 s3, s2, 6
	s_cmp_ge_i32 s3, s89
	global_load_dword v42, v[22:23], off
	v_lshl_add_u64 v[22:23], v[114:115], 0, s[4:5]
	s_cselect_b64 s[4:5], -1, 0
	s_cmp_lt_i32 s3, s88
	s_cselect_b64 s[8:9], -1, 0
	s_and_b64 s[44:45], s[4:5], s[8:9]
	s_and_b64 s[4:5], s[44:45], exec
	s_cselect_b32 s4, s3, s2
	s_ashr_i32 s5, s4, 31
	s_lshl_b64 s[4:5], s[4:5], 11
	s_add_i32 s3, s2, 7
	s_cmp_ge_i32 s3, s89
	global_load_dword v39, v[22:23], off
	v_lshl_add_u64 v[22:23], v[114:115], 0, s[4:5]
	s_cselect_b64 s[4:5], -1, 0
	s_cmp_lt_i32 s3, s88
	s_cselect_b64 s[8:9], -1, 0
	s_and_b64 s[38:39], s[4:5], s[8:9]
	s_and_b64 s[4:5], s[38:39], exec
	s_cselect_b32 s4, s3, s2
	s_ashr_i32 s5, s4, 31
	s_lshl_b64 s[4:5], s[4:5], 11
	s_add_i32 s3, s2, 8
	s_cmp_ge_i32 s3, s89
	global_load_dword v36, v[22:23], off
	v_lshl_add_u64 v[22:23], v[114:115], 0, s[4:5]
	s_cselect_b64 s[4:5], -1, 0
	s_cmp_lt_i32 s3, s88
	s_cselect_b64 s[8:9], -1, 0
	s_and_b64 s[24:25], s[4:5], s[8:9]
	s_and_b64 s[4:5], s[24:25], exec
	s_cselect_b32 s4, s3, s2
	s_ashr_i32 s5, s4, 31
	s_lshl_b64 s[4:5], s[4:5], 11
	s_add_i32 s3, s2, 9
	s_cmp_ge_i32 s3, s89
	global_load_dword v33, v[22:23], off
	v_lshl_add_u64 v[22:23], v[114:115], 0, s[4:5]
	s_cselect_b64 s[4:5], -1, 0
	s_cmp_lt_i32 s3, s88
	s_cselect_b64 s[8:9], -1, 0
	s_and_b64 s[54:55], s[4:5], s[8:9]
	s_and_b64 s[4:5], s[54:55], exec
	s_cselect_b32 s4, s3, s2
	s_ashr_i32 s5, s4, 31
	s_lshl_b64 s[4:5], s[4:5], 11
	s_add_i32 s3, s2, 10
	s_cmp_ge_i32 s3, s89
	global_load_dword v40, v[22:23], off
	v_lshl_add_u64 v[22:23], v[114:115], 0, s[4:5]
	s_cselect_b64 s[4:5], -1, 0
	s_cmp_lt_i32 s3, s88
	s_cselect_b64 s[8:9], -1, 0
	s_and_b64 s[48:49], s[4:5], s[8:9]
	s_and_b64 s[4:5], s[48:49], exec
	s_cselect_b32 s4, s3, s2
	s_ashr_i32 s5, s4, 31
	s_lshl_b64 s[4:5], s[4:5], 11
	s_add_i32 s3, s2, 11
	s_cmp_ge_i32 s3, s89
	global_load_dword v41, v[22:23], off
	v_lshl_add_u64 v[22:23], v[114:115], 0, s[4:5]
	s_cselect_b64 s[4:5], -1, 0
	s_cmp_lt_i32 s3, s88
	s_cselect_b64 s[8:9], -1, 0
	s_and_b64 s[42:43], s[4:5], s[8:9]
	s_and_b64 s[4:5], s[42:43], exec
	s_cselect_b32 s4, s3, s2
	s_ashr_i32 s5, s4, 31
	s_lshl_b64 s[4:5], s[4:5], 11
	s_add_i32 s3, s2, 12
	s_cmp_ge_i32 s3, s89
	global_load_dword v37, v[22:23], off
	v_lshl_add_u64 v[22:23], v[114:115], 0, s[4:5]
	s_cselect_b64 s[4:5], -1, 0
	s_cmp_lt_i32 s3, s88
	s_cselect_b64 s[8:9], -1, 0
	s_and_b64 s[34:35], s[4:5], s[8:9]
	s_and_b64 s[4:5], s[34:35], exec
	s_cselect_b32 s4, s3, s2
	s_ashr_i32 s5, s4, 31
	s_lshl_b64 s[4:5], s[4:5], 11
	s_add_i32 s3, s2, 13
	s_cmp_ge_i32 s3, s89
	global_load_dword v35, v[22:23], off
	v_lshl_add_u64 v[22:23], v[114:115], 0, s[4:5]
	s_cselect_b64 s[4:5], -1, 0
	s_cmp_lt_i32 s3, s88
	s_cselect_b64 s[8:9], -1, 0
	s_and_b64 s[14:15], s[4:5], s[8:9]
	s_and_b64 s[4:5], s[14:15], exec
	s_cselect_b32 s4, s3, s2
	s_ashr_i32 s5, s4, 31
	s_lshl_b64 s[4:5], s[4:5], 11
	s_add_i32 s3, s2, 14
	s_cmp_ge_i32 s3, s89
	global_load_dword v30, v[22:23], off
	v_lshl_add_u64 v[22:23], v[114:115], 0, s[4:5]
	s_cselect_b64 s[4:5], -1, 0
	s_cmp_lt_i32 s3, s88
	s_cselect_b64 s[8:9], -1, 0
	s_and_b64 s[10:11], s[4:5], s[8:9]
	s_and_b64 s[4:5], s[10:11], exec
	s_cselect_b32 s4, s3, s2
	s_ashr_i32 s5, s4, 31
	s_lshl_b64 s[4:5], s[4:5], 11
	s_add_i32 s3, s2, 15
	s_cmp_ge_i32 s3, s89
	v_lshl_add_u64 v[24:25], v[114:115], 0, s[4:5]
	s_cselect_b64 s[4:5], -1, 0
	s_cmp_lt_i32 s3, s88
	s_cselect_b64 s[8:9], -1, 0
	s_and_b64 s[8:9], s[4:5], s[8:9]
	s_and_b64 s[4:5], s[8:9], exec
	s_cselect_b32 s4, s3, s2
	s_ashr_i32 s5, s4, 31
	s_lshl_b64 s[4:5], s[4:5], 11
	s_add_i32 s3, s2, 16
	s_cmp_ge_i32 s3, s89
	global_load_dword v22, v[22:23], off
	s_nop 0
	global_load_dword v20, v[24:25], off
	v_lshl_add_u64 v[24:25], v[114:115], 0, s[4:5]
	s_cselect_b64 s[4:5], -1, 0
	s_cmp_lt_i32 s3, s88
	s_cselect_b64 s[16:17], -1, 0
	s_and_b64 s[4:5], s[4:5], s[16:17]
	s_and_b64 s[16:17], s[4:5], exec
	s_cselect_b32 s16, s3, s2
	s_ashr_i32 s17, s16, 31
	s_lshl_b64 s[16:17], s[16:17], 11
	s_add_i32 s3, s2, 17
	s_cmp_ge_i32 s3, s89
	global_load_dword v19, v[24:25], off
	v_lshl_add_u64 v[24:25], v[114:115], 0, s[16:17]
	s_cselect_b64 s[16:17], -1, 0
	s_cmp_lt_i32 s3, s88
	s_cselect_b64 s[18:19], -1, 0
	s_and_b64 s[26:27], s[16:17], s[18:19]
	s_and_b64 s[16:17], s[26:27], exec
	s_cselect_b32 s16, s3, s2
	s_ashr_i32 s17, s16, 31
	s_lshl_b64 s[16:17], s[16:17], 11
	s_add_i32 s3, s2, 18
	s_cmp_ge_i32 s3, s89
	global_load_dword v27, v[24:25], off
	v_lshl_add_u64 v[24:25], v[114:115], 0, s[16:17]
	s_cselect_b64 s[16:17], -1, 0
	s_cmp_lt_i32 s3, s88
	s_cselect_b64 s[18:19], -1, 0
	s_and_b64 s[20:21], s[16:17], s[18:19]
	s_and_b64 s[16:17], s[20:21], exec
	s_cselect_b32 s16, s3, s2
	s_ashr_i32 s17, s16, 31
	s_lshl_b64 s[16:17], s[16:17], 11
	s_add_i32 s3, s2, 19
	s_cmp_ge_i32 s3, s89
	global_load_dword v31, v[24:25], off
	v_lshl_add_u64 v[24:25], v[114:115], 0, s[16:17]
	s_cselect_b64 s[16:17], -1, 0
	s_cmp_lt_i32 s3, s88
	s_cselect_b64 s[18:19], -1, 0
	s_and_b64 s[16:17], s[16:17], s[18:19]
	s_and_b64 s[18:19], s[16:17], exec
	s_cselect_b32 s18, s3, s2
	s_ashr_i32 s19, s18, 31
	s_lshl_b64 s[18:19], s[18:19], 11
	s_add_i32 s3, s2, 20
	s_cmp_ge_i32 s3, s89
	v_lshl_add_u64 v[140:141], v[114:115], 0, s[18:19]
	s_cselect_b64 s[18:19], -1, 0
	s_cmp_lt_i32 s3, s88
	s_cselect_b64 s[22:23], -1, 0
	s_and_b64 s[18:19], s[18:19], s[22:23]
	s_and_b64 s[22:23], s[18:19], exec
	s_cselect_b32 s22, s3, s2
	s_ashr_i32 s23, s22, 31
	s_lshl_b64 s[22:23], s[22:23], 11
	s_add_i32 s3, s2, 21
	s_cmp_ge_i32 s3, s89
	global_load_dword v25, v[24:25], off
	s_nop 0
	global_load_dword v23, v[140:141], off
	v_lshl_add_u64 v[140:141], v[114:115], 0, s[22:23]
	s_cselect_b64 s[22:23], -1, 0
	s_cmp_lt_i32 s3, s88
	s_cselect_b64 s[28:29], -1, 0
	s_and_b64 s[22:23], s[22:23], s[28:29]
	s_and_b64 s[28:29], s[22:23], exec
	s_cselect_b32 s28, s3, s2
	s_ashr_i32 s29, s28, 31
	s_lshl_b64 s[28:29], s[28:29], 11
	s_add_i32 s3, s2, 22
	s_cmp_ge_i32 s3, s89
	global_load_dword v24, v[140:141], off
	v_lshl_add_u64 v[140:141], v[114:115], 0, s[28:29]
	s_cselect_b64 s[28:29], -1, 0
	s_cmp_lt_i32 s3, s88
	s_cselect_b64 s[40:41], -1, 0
	s_and_b64 s[28:29], s[28:29], s[40:41]
	s_and_b64 s[40:41], s[28:29], exec
	s_cselect_b32 s40, s3, s2
	s_ashr_i32 s41, s40, 31
	s_lshl_b64 s[40:41], s[40:41], 11
	s_add_i32 s3, s2, 23
	s_cmp_ge_i32 s3, s89
	global_load_dword v26, v[140:141], off
	v_lshl_add_u64 v[140:141], v[114:115], 0, s[40:41]
	s_cselect_b64 s[40:41], -1, 0
	s_cmp_lt_i32 s3, s88
	s_cselect_b64 s[46:47], -1, 0
	s_and_b64 s[40:41], s[40:41], s[46:47]
	s_and_b64 s[46:47], s[40:41], exec
	s_cselect_b32 s46, s3, s2
	s_ashr_i32 s47, s46, 31
	s_lshl_b64 s[46:47], s[46:47], 11
	s_add_i32 s3, s2, 24
	s_cmp_ge_i32 s3, s89
	global_load_dword v28, v[140:141], off
	v_lshl_add_u64 v[140:141], v[114:115], 0, s[46:47]
	s_cselect_b64 s[46:47], -1, 0
	s_cmp_lt_i32 s3, s88
	s_cselect_b64 s[66:67], -1, 0
	s_and_b64 s[46:47], s[46:47], s[66:67]
	s_and_b64 s[66:67], s[46:47], exec
	s_cselect_b32 s66, s3, s2
	s_ashr_i32 s67, s66, 31
	s_lshl_b64 s[66:67], s[66:67], 11
	s_add_i32 s3, s2, 25
	s_cmp_ge_i32 s3, s89
	global_load_dword v34, v[140:141], off
	v_lshl_add_u64 v[140:141], v[114:115], 0, s[66:67]
	s_cselect_b64 s[66:67], -1, 0
	s_cmp_lt_i32 s3, s88
	s_cselect_b64 s[68:69], -1, 0
	s_and_b64 s[66:67], s[66:67], s[68:69]
	s_and_b64 s[68:69], s[66:67], exec
	s_cselect_b32 s68, s3, s2
	s_ashr_i32 s69, s68, 31
	s_lshl_b64 s[68:69], s[68:69], 11
	s_add_i32 s3, s2, 26
	s_cmp_ge_i32 s3, s89
	global_load_dword v45, v[140:141], off
	v_lshl_add_u64 v[140:141], v[114:115], 0, s[68:69]
	s_cselect_b64 s[68:69], -1, 0
	s_cmp_lt_i32 s3, s88
	s_cselect_b64 s[72:73], -1, 0
	s_and_b64 s[68:69], s[68:69], s[72:73]
	s_and_b64 s[72:73], s[68:69], exec
	s_cselect_b32 s72, s3, s2
	s_ashr_i32 s73, s72, 31
	s_lshl_b64 s[72:73], s[72:73], 11
	s_add_i32 s3, s2, 27
	s_cmp_ge_i32 s3, s89
	global_load_dword v118, v[140:141], off
	v_lshl_add_u64 v[140:141], v[114:115], 0, s[72:73]
	s_cselect_b64 s[72:73], -1, 0
	s_cmp_lt_i32 s3, s88
	s_cselect_b64 s[80:81], -1, 0
	s_and_b64 s[72:73], s[72:73], s[80:81]
	s_and_b64 s[80:81], s[72:73], exec
	s_cselect_b32 s80, s3, s2
	s_ashr_i32 s81, s80, 31
	s_lshl_b64 s[80:81], s[80:81], 11
	s_add_i32 s3, s2, 28
	s_cmp_ge_i32 s3, s89
	global_load_dword v120, v[140:141], off
	v_lshl_add_u64 v[140:141], v[114:115], 0, s[80:81]
	s_cselect_b64 s[80:81], -1, 0
	s_cmp_lt_i32 s3, s88
	s_cselect_b64 s[82:83], -1, 0
	s_and_b64 s[80:81], s[80:81], s[82:83]
	s_and_b64 s[82:83], s[80:81], exec
	s_cselect_b32 s82, s3, s2
	s_ashr_i32 s83, s82, 31
	s_lshl_b64 s[82:83], s[82:83], 11
	s_add_i32 s3, s2, 29
	s_cmp_ge_i32 s3, s89
	global_load_dword v133, v[140:141], off
	v_lshl_add_u64 v[140:141], v[114:115], 0, s[82:83]
	s_cselect_b64 s[82:83], -1, 0
	s_cmp_lt_i32 s3, s88
	s_cselect_b64 s[84:85], -1, 0
	s_and_b64 s[82:83], s[82:83], s[84:85]
	s_and_b64 s[84:85], s[82:83], exec
	s_cselect_b32 s84, s3, s2
	s_ashr_i32 s85, s84, 31
	s_lshl_b64 s[84:85], s[84:85], 11
	s_add_i32 s3, s2, 30
	s_cmp_ge_i32 s3, s89
	global_load_dword v139, v[140:141], off
	v_lshl_add_u64 v[140:141], v[114:115], 0, s[84:85]
	s_cselect_b64 s[84:85], -1, 0
	s_cmp_lt_i32 s3, s88
	s_cselect_b64 s[86:87], -1, 0
	s_and_b64 s[84:85], s[84:85], s[86:87]
	s_and_b64 s[86:87], s[84:85], exec
	s_cselect_b32 s86, s3, s2
	s_ashr_i32 s87, s86, 31
	s_lshl_b64 s[86:87], s[86:87], 11
	v_lshl_add_u64 v[142:143], v[114:115], 0, s[86:87]
	global_load_dword v140, v[140:141], off
	s_movk_i32 s86, 0x4000
	global_load_dword v141, v[142:143], off
	s_waitcnt vmcnt(45)
	v_lshlrev_b32_e32 v142, 16, v0
	v_and_b32_e32 v0, 0xffff0000, v0
	v_cndmask_b32_e64 v143, 0, v0, s[0:1]
	s_waitcnt vmcnt(44)
	v_lshlrev_b32_e32 v0, 16, v18
	v_cndmask_b32_e64 v144, 0, v0, s[6:7]
	v_and_b32_e32 v0, 0xffff0000, v18
	v_cndmask_b32_e64 v145, 0, v0, s[6:7]
	s_waitcnt vmcnt(43)
	v_lshlrev_b32_e32 v0, 16, v21
	v_cndmask_b32_e64 v146, 0, v0, s[12:13]
	v_and_b32_e32 v0, 0xffff0000, v21
	v_cndmask_b32_e64 v147, 0, v0, s[12:13]
	s_waitcnt vmcnt(42)
	v_lshlrev_b32_e32 v0, 16, v29
	v_cndmask_b32_e64 v148, 0, v0, s[30:31]
	v_and_b32_e32 v0, 0xffff0000, v29
	v_cndmask_b32_e64 v149, 0, v0, s[30:31]
	s_waitcnt vmcnt(41)
	v_lshlrev_b32_e32 v0, 16, v32
	v_cndmask_b32_e64 v152, 0, v0, s[36:37]
	v_and_b32_e32 v0, 0xffff0000, v32
	v_cndmask_b32_e64 v153, 0, v0, s[36:37]
	s_waitcnt vmcnt(40)
	v_lshlrev_b32_e32 v0, 16, v38
	v_cndmask_b32_e64 v154, 0, v0, s[50:51]
	v_and_b32_e32 v0, 0xffff0000, v38
	v_cndmask_b32_e64 v155, 0, v0, s[50:51]
	s_waitcnt vmcnt(39)
	v_lshlrev_b32_e32 v0, 16, v43
	v_cndmask_b32_e64 v156, 0, v0, s[58:59]
	v_and_b32_e32 v0, 0xffff0000, v43
	v_cndmask_b32_e64 v142, 0, v142, s[0:1]
	v_cndmask_b32_e64 v157, 0, v0, s[58:59]
	s_waitcnt vmcnt(38)
	v_lshlrev_b32_e32 v0, 16, v119
	v_pk_fma_f32 v[142:143], v[54:55], v[142:143], v[112:113]
	v_cndmask_b32_e32 v158, 0, v0, vcc
	v_and_b32_e32 v0, 0xffff0000, v119
	v_pk_fma_f32 v[142:143], v[56:57], v[144:145], v[142:143]
	v_pk_fma_f32 v[144:145], v[54:55], v[144:145], v[112:113]
	v_cndmask_b32_e32 v159, 0, v0, vcc
	s_waitcnt vmcnt(37)
	v_lshlrev_b32_e32 v0, 16, v134
	v_pk_fma_f32 v[142:143], v[58:59], v[146:147], v[142:143]
	v_pk_fma_f32 v[144:145], v[56:57], v[146:147], v[144:145]
	v_pk_fma_f32 v[146:147], v[54:55], v[146:147], v[112:113]
	v_cndmask_b32_e64 v160, 0, v0, s[70:71]
	v_and_b32_e32 v0, 0xffff0000, v134
	v_pk_fma_f32 v[142:143], v[50:51], v[148:149], v[142:143]
	v_pk_fma_f32 v[144:145], v[58:59], v[148:149], v[144:145]
	v_pk_fma_f32 v[146:147], v[56:57], v[148:149], v[146:147]
	v_pk_fma_f32 v[148:149], v[54:55], v[148:149], v[112:113]
	v_cndmask_b32_e64 v161, 0, v0, s[70:71]
	s_waitcnt vmcnt(36)
	v_lshlrev_b32_e32 v0, 16, v137
	v_pk_fma_f32 v[142:143], v[52:53], v[152:153], v[142:143]
	v_pk_fma_f32 v[144:145], v[50:51], v[152:153], v[144:145]
	v_pk_fma_f32 v[146:147], v[58:59], v[152:153], v[146:147]
	v_pk_fma_f32 v[148:149], v[56:57], v[152:153], v[148:149]
	v_pk_fma_f32 v[152:153], v[54:55], v[152:153], v[112:113]
	v_cndmask_b32_e64 v162, 0, v0, s[76:77]
	v_and_b32_e32 v0, 0xffff0000, v137
	v_pk_fma_f32 v[142:143], v[60:61], v[154:155], v[142:143]
	v_pk_fma_f32 v[144:145], v[52:53], v[154:155], v[144:145]
	v_pk_fma_f32 v[146:147], v[50:51], v[154:155], v[146:147]
	v_pk_fma_f32 v[148:149], v[58:59], v[154:155], v[148:149]
	v_pk_fma_f32 v[152:153], v[56:57], v[154:155], v[152:153]
	v_pk_fma_f32 v[154:155], v[54:55], v[154:155], v[112:113]
	v_cndmask_b32_e64 v163, 0, v0, s[76:77]
	s_waitcnt vmcnt(35)
	v_lshlrev_b32_e32 v0, 16, v138
	v_pk_fma_f32 v[142:143], v[62:63], v[156:157], v[142:143]
	v_pk_fma_f32 v[144:145], v[60:61], v[156:157], v[144:145]
	v_pk_fma_f32 v[146:147], v[52:53], v[156:157], v[146:147]
	v_pk_fma_f32 v[148:149], v[50:51], v[156:157], v[148:149]
	v_pk_fma_f32 v[152:153], v[58:59], v[156:157], v[152:153]
	v_pk_fma_f32 v[154:155], v[56:57], v[156:157], v[154:155]
	v_pk_fma_f32 v[156:157], v[54:55], v[156:157], v[112:113]
	v_cndmask_b32_e64 v164, 0, v0, s[78:79]
	v_and_b32_e32 v0, 0xffff0000, v138
	v_pk_fma_f32 v[142:143], v[64:65], v[158:159], v[142:143]
	v_pk_fma_f32 v[144:145], v[62:63], v[158:159], v[144:145]
	v_pk_fma_f32 v[146:147], v[60:61], v[158:159], v[146:147]
	v_pk_fma_f32 v[148:149], v[52:53], v[158:159], v[148:149]
	v_pk_fma_f32 v[152:153], v[50:51], v[158:159], v[152:153]
	v_pk_fma_f32 v[154:155], v[58:59], v[158:159], v[154:155]
	v_pk_fma_f32 v[156:157], v[56:57], v[158:159], v[156:157]
	v_pk_fma_f32 v[158:159], v[54:55], v[158:159], v[112:113]
	v_cndmask_b32_e64 v165, 0, v0, s[78:79]
	s_waitcnt vmcnt(34)
	v_lshlrev_b32_e32 v0, 16, v135
	v_pk_fma_f32 v[142:143], v[66:67], v[160:161], v[142:143]
	v_pk_fma_f32 v[144:145], v[64:65], v[160:161], v[144:145]
	v_pk_fma_f32 v[146:147], v[62:63], v[160:161], v[146:147]
	v_pk_fma_f32 v[148:149], v[60:61], v[160:161], v[148:149]
	v_pk_fma_f32 v[152:153], v[52:53], v[160:161], v[152:153]
	v_pk_fma_f32 v[154:155], v[50:51], v[160:161], v[154:155]
	v_pk_fma_f32 v[156:157], v[58:59], v[160:161], v[156:157]
	v_pk_fma_f32 v[158:159], v[56:57], v[160:161], v[158:159]
	v_pk_fma_f32 v[160:161], v[54:55], v[160:161], v[112:113]
	v_cndmask_b32_e32 v134, 0, v0, vcc
	v_and_b32_e32 v0, 0xffff0000, v135
	v_pk_fma_f32 v[142:143], v[68:69], v[162:163], v[142:143]
	v_pk_fma_f32 v[144:145], v[66:67], v[162:163], v[144:145]
	v_pk_fma_f32 v[146:147], v[64:65], v[162:163], v[146:147]
	v_pk_fma_f32 v[148:149], v[62:63], v[162:163], v[148:149]
	v_pk_fma_f32 v[152:153], v[60:61], v[162:163], v[152:153]
	v_pk_fma_f32 v[154:155], v[52:53], v[162:163], v[154:155]
	v_pk_fma_f32 v[156:157], v[50:51], v[162:163], v[156:157]
	v_pk_fma_f32 v[158:159], v[58:59], v[162:163], v[158:159]
	v_pk_fma_f32 v[160:161], v[56:57], v[162:163], v[160:161]
	v_pk_fma_f32 v[162:163], v[54:55], v[162:163], v[112:113]
	v_cndmask_b32_e32 v135, 0, v0, vcc
	s_waitcnt vmcnt(33)
	v_lshlrev_b32_e32 v0, 16, v136
	v_pk_fma_f32 v[142:143], v[70:71], v[164:165], v[142:143]
	v_pk_fma_f32 v[144:145], v[68:69], v[164:165], v[144:145]
	v_pk_fma_f32 v[146:147], v[66:67], v[164:165], v[146:147]
	v_pk_fma_f32 v[148:149], v[64:65], v[164:165], v[148:149]
	v_pk_fma_f32 v[152:153], v[62:63], v[164:165], v[152:153]
	v_pk_fma_f32 v[154:155], v[60:61], v[164:165], v[154:155]
	v_pk_fma_f32 v[156:157], v[52:53], v[164:165], v[156:157]
	v_pk_fma_f32 v[158:159], v[50:51], v[164:165], v[158:159]
	v_pk_fma_f32 v[160:161], v[58:59], v[164:165], v[160:161]
	v_pk_fma_f32 v[162:163], v[56:57], v[164:165], v[162:163]
	v_pk_fma_f32 v[164:165], v[54:55], v[164:165], v[112:113]
	v_cndmask_b32_e64 v166, 0, v0, s[74:75]
	v_and_b32_e32 v0, 0xffff0000, v136
	v_pk_fma_f32 v[142:143], v[72:73], v[134:135], v[142:143]
	v_pk_fma_f32 v[144:145], v[70:71], v[134:135], v[144:145]
	v_pk_fma_f32 v[146:147], v[68:69], v[134:135], v[146:147]
	v_pk_fma_f32 v[148:149], v[66:67], v[134:135], v[148:149]
	v_pk_fma_f32 v[152:153], v[64:65], v[134:135], v[152:153]
	v_pk_fma_f32 v[154:155], v[62:63], v[134:135], v[154:155]
	v_pk_fma_f32 v[156:157], v[60:61], v[134:135], v[156:157]
	v_pk_fma_f32 v[158:159], v[52:53], v[134:135], v[158:159]
	v_pk_fma_f32 v[160:161], v[50:51], v[134:135], v[160:161]
	v_pk_fma_f32 v[162:163], v[58:59], v[134:135], v[162:163]
	v_pk_fma_f32 v[164:165], v[56:57], v[134:135], v[164:165]
	v_pk_fma_f32 v[134:135], v[54:55], v[134:135], v[112:113]
	v_cndmask_b32_e64 v167, 0, v0, s[74:75]
	s_waitcnt vmcnt(32)
	v_lshlrev_b32_e32 v0, 16, v121
	v_pk_fma_f32 v[136:137], v[74:75], v[166:167], v[142:143]
	v_pk_fma_f32 v[142:143], v[72:73], v[166:167], v[144:145]
	v_pk_fma_f32 v[144:145], v[70:71], v[166:167], v[146:147]
	v_pk_fma_f32 v[146:147], v[68:69], v[166:167], v[148:149]
	v_pk_fma_f32 v[148:149], v[66:67], v[166:167], v[152:153]
	v_pk_fma_f32 v[152:153], v[64:65], v[166:167], v[154:155]
	v_pk_fma_f32 v[154:155], v[62:63], v[166:167], v[156:157]
	v_pk_fma_f32 v[156:157], v[60:61], v[166:167], v[158:159]
	v_pk_fma_f32 v[158:159], v[52:53], v[166:167], v[160:161]
	v_pk_fma_f32 v[160:161], v[50:51], v[166:167], v[162:163]
	v_pk_fma_f32 v[162:163], v[58:59], v[166:167], v[164:165]
	v_pk_fma_f32 v[134:135], v[56:57], v[166:167], v[134:135]
	v_pk_fma_f32 v[164:165], v[54:55], v[166:167], v[112:113]
	v_cndmask_b32_e32 v166, 0, v0, vcc
	v_and_b32_e32 v0, 0xffff0000, v121
	s_cmp_ge_i32 s2, s89
	v_cndmask_b32_e32 v167, 0, v0, vcc
	s_waitcnt vmcnt(31)
	v_lshlrev_b32_e32 v0, 16, v49
	s_cselect_b64 s[0:1], -1, 0
	s_cmp_lt_i32 s2, s88
	v_cndmask_b32_e32 v168, 0, v0, vcc
	v_and_b32_e32 v0, 0xffff0000, v49
	s_cselect_b64 s[6:7], -1, 0
	v_cndmask_b32_e32 v169, 0, v0, vcc
	s_waitcnt vmcnt(30)
	v_lshlrev_b32_e32 v0, 16, v47
	s_and_b64 vcc, s[0:1], s[6:7]
	v_cndmask_b32_e32 v170, 0, v0, vcc
	v_and_b32_e32 v0, 0xffff0000, v47
	v_pk_fma_f32 v[136:137], v[76:77], v[166:167], v[136:137]
	v_pk_fma_f32 v[142:143], v[74:75], v[166:167], v[142:143]
	v_pk_fma_f32 v[144:145], v[72:73], v[166:167], v[144:145]
	v_pk_fma_f32 v[146:147], v[70:71], v[166:167], v[146:147]
	v_pk_fma_f32 v[148:149], v[68:69], v[166:167], v[148:149]
	v_pk_fma_f32 v[152:153], v[66:67], v[166:167], v[152:153]
	v_pk_fma_f32 v[154:155], v[64:65], v[166:167], v[154:155]
	v_pk_fma_f32 v[156:157], v[62:63], v[166:167], v[156:157]
	v_pk_fma_f32 v[158:159], v[60:61], v[166:167], v[158:159]
	v_pk_fma_f32 v[160:161], v[52:53], v[166:167], v[160:161]
	v_pk_fma_f32 v[162:163], v[50:51], v[166:167], v[162:163]
	v_pk_fma_f32 v[134:135], v[58:59], v[166:167], v[134:135]
	v_pk_fma_f32 v[164:165], v[56:57], v[166:167], v[164:165]
	v_pk_fma_f32 v[166:167], v[54:55], v[166:167], v[112:113]
	v_cndmask_b32_e32 v171, 0, v0, vcc
	s_waitcnt vmcnt(29)
	v_lshlrev_b32_e32 v0, 16, v48
	v_pk_fma_f32 v[136:137], v[78:79], v[168:169], v[136:137]
	v_pk_fma_f32 v[142:143], v[76:77], v[168:169], v[142:143]
	v_pk_fma_f32 v[144:145], v[74:75], v[168:169], v[144:145]
	v_pk_fma_f32 v[146:147], v[72:73], v[168:169], v[146:147]
	v_pk_fma_f32 v[148:149], v[70:71], v[168:169], v[148:149]
	v_pk_fma_f32 v[152:153], v[68:69], v[168:169], v[152:153]
	v_pk_fma_f32 v[154:155], v[66:67], v[168:169], v[154:155]
	v_pk_fma_f32 v[156:157], v[64:65], v[168:169], v[156:157]
	v_pk_fma_f32 v[158:159], v[62:63], v[168:169], v[158:159]
	v_pk_fma_f32 v[160:161], v[60:61], v[168:169], v[160:161]
	v_pk_fma_f32 v[162:163], v[52:53], v[168:169], v[162:163]
	v_pk_fma_f32 v[134:135], v[50:51], v[168:169], v[134:135]
	v_pk_fma_f32 v[164:165], v[58:59], v[168:169], v[164:165]
	v_pk_fma_f32 v[166:167], v[56:57], v[168:169], v[166:167]
	v_pk_fma_f32 v[168:169], v[54:55], v[168:169], v[112:113]
	v_cndmask_b32_e64 v172, 0, v0, s[64:65]
	v_and_b32_e32 v0, 0xffff0000, v48
	v_pk_fma_f32 v[136:137], v[80:81], v[170:171], v[136:137]
	v_pk_fma_f32 v[142:143], v[78:79], v[170:171], v[142:143]
	v_pk_fma_f32 v[144:145], v[76:77], v[170:171], v[144:145]
	v_pk_fma_f32 v[146:147], v[74:75], v[170:171], v[146:147]
	v_pk_fma_f32 v[148:149], v[72:73], v[170:171], v[148:149]
	v_pk_fma_f32 v[152:153], v[70:71], v[170:171], v[152:153]
	v_pk_fma_f32 v[154:155], v[68:69], v[170:171], v[154:155]
	v_pk_fma_f32 v[156:157], v[66:67], v[170:171], v[156:157]
	v_pk_fma_f32 v[158:159], v[64:65], v[170:171], v[158:159]
	v_pk_fma_f32 v[160:161], v[62:63], v[170:171], v[160:161]
	v_pk_fma_f32 v[162:163], v[60:61], v[170:171], v[162:163]
	v_pk_fma_f32 v[134:135], v[52:53], v[170:171], v[134:135]
	v_pk_fma_f32 v[164:165], v[50:51], v[170:171], v[164:165]
	v_pk_fma_f32 v[166:167], v[58:59], v[170:171], v[166:167]
	v_pk_fma_f32 v[168:169], v[56:57], v[170:171], v[168:169]
	v_pk_fma_f32 v[170:171], v[54:55], v[170:171], v[112:113]
	v_cndmask_b32_e64 v173, 0, v0, s[64:65]
	s_waitcnt vmcnt(28)
	v_lshlrev_b32_e32 v0, 16, v46
	v_pk_fma_f32 v[48:49], v[82:83], v[172:173], v[136:137]
	v_pk_fma_f32 v[136:137], v[80:81], v[172:173], v[142:143]
	v_pk_fma_f32 v[142:143], v[78:79], v[172:173], v[144:145]
	v_pk_fma_f32 v[144:145], v[76:77], v[172:173], v[146:147]
	v_pk_fma_f32 v[146:147], v[74:75], v[172:173], v[148:149]
	v_pk_fma_f32 v[148:149], v[72:73], v[172:173], v[152:153]
	v_pk_fma_f32 v[152:153], v[70:71], v[172:173], v[154:155]
	v_pk_fma_f32 v[154:155], v[68:69], v[172:173], v[156:157]
	v_pk_fma_f32 v[156:157], v[66:67], v[172:173], v[158:159]
	v_pk_fma_f32 v[158:159], v[64:65], v[172:173], v[160:161]
	v_pk_fma_f32 v[160:161], v[62:63], v[172:173], v[162:163]
	v_pk_fma_f32 v[162:163], v[52:53], v[172:173], v[164:165]
	v_pk_fma_f32 v[164:165], v[50:51], v[172:173], v[166:167]
	v_pk_fma_f32 v[166:167], v[58:59], v[172:173], v[168:169]
	v_pk_fma_f32 v[168:169], v[56:57], v[172:173], v[170:171]
	v_cndmask_b32_e64 v170, 0, v0, s[62:63]
	v_and_b32_e32 v0, 0xffff0000, v46
	v_cndmask_b32_e64 v171, 0, v0, s[62:63]
	s_waitcnt vmcnt(27)
	v_lshlrev_b32_e32 v0, 16, v44
	v_pk_fma_f32 v[134:135], v[60:61], v[172:173], v[134:135]
	v_pk_fma_f32 v[46:47], v[84:85], v[170:171], v[48:49]
	v_pk_fma_f32 v[48:49], v[82:83], v[170:171], v[136:137]
	v_pk_fma_f32 v[136:137], v[80:81], v[170:171], v[142:143]
	v_pk_fma_f32 v[142:143], v[78:79], v[170:171], v[144:145]
	v_pk_fma_f32 v[144:145], v[76:77], v[170:171], v[146:147]
	v_pk_fma_f32 v[146:147], v[74:75], v[170:171], v[148:149]
	v_pk_fma_f32 v[148:149], v[72:73], v[170:171], v[152:153]
	v_pk_fma_f32 v[152:153], v[70:71], v[170:171], v[154:155]
	v_pk_fma_f32 v[154:155], v[68:69], v[170:171], v[156:157]
	v_pk_fma_f32 v[156:157], v[66:67], v[170:171], v[158:159]
	v_pk_fma_f32 v[158:159], v[64:65], v[170:171], v[160:161]
	v_pk_fma_f32 v[160:161], v[60:61], v[170:171], v[162:163]
	v_pk_fma_f32 v[162:163], v[52:53], v[170:171], v[164:165]
	v_pk_fma_f32 v[164:165], v[50:51], v[170:171], v[166:167]
	v_pk_fma_f32 v[166:167], v[58:59], v[170:171], v[168:169]
	v_cndmask_b32_e64 v168, 0, v0, s[60:61]
	v_and_b32_e32 v0, 0xffff0000, v44
	v_pk_fma_f32 v[134:135], v[62:63], v[170:171], v[134:135]
	v_cndmask_b32_e64 v169, 0, v0, s[60:61]
	s_waitcnt vmcnt(26)
	v_lshlrev_b32_e32 v0, 16, v42
	v_pk_fma_f32 v[46:47], v[86:87], v[168:169], v[46:47]
	v_pk_fma_f32 v[48:49], v[84:85], v[168:169], v[48:49]
	v_pk_fma_f32 v[136:137], v[82:83], v[168:169], v[136:137]
	v_pk_fma_f32 v[142:143], v[80:81], v[168:169], v[142:143]
	v_pk_fma_f32 v[144:145], v[78:79], v[168:169], v[144:145]
	v_pk_fma_f32 v[146:147], v[76:77], v[168:169], v[146:147]
	v_pk_fma_f32 v[148:149], v[74:75], v[168:169], v[148:149]
	v_pk_fma_f32 v[152:153], v[72:73], v[168:169], v[152:153]
	v_pk_fma_f32 v[154:155], v[70:71], v[168:169], v[154:155]
	v_pk_fma_f32 v[156:157], v[68:69], v[168:169], v[156:157]
	v_pk_fma_f32 v[158:159], v[66:67], v[168:169], v[158:159]
	v_pk_fma_f32 v[134:135], v[64:65], v[168:169], v[134:135]
	v_pk_fma_f32 v[160:161], v[62:63], v[168:169], v[160:161]
	v_pk_fma_f32 v[162:163], v[60:61], v[168:169], v[162:163]
	v_pk_fma_f32 v[164:165], v[52:53], v[168:169], v[164:165]
	v_pk_fma_f32 v[166:167], v[50:51], v[168:169], v[166:167]
	v_cndmask_b32_e64 v168, 0, v0, s[56:57]
	v_and_b32_e32 v0, 0xffff0000, v42
	v_cndmask_b32_e64 v169, 0, v0, s[56:57]
	s_waitcnt vmcnt(25)
	v_lshlrev_b32_e32 v0, 16, v39
	v_cndmask_b32_e64 v38, 0, v0, s[52:53]
	v_and_b32_e32 v0, 0xffff0000, v39
	v_pk_fma_f32 v[42:43], v[88:89], v[168:169], v[46:47]
	v_pk_fma_f32 v[46:47], v[86:87], v[168:169], v[48:49]
	v_pk_fma_f32 v[48:49], v[84:85], v[168:169], v[136:137]
	v_pk_fma_f32 v[136:137], v[82:83], v[168:169], v[142:143]
	v_pk_fma_f32 v[142:143], v[80:81], v[168:169], v[144:145]
	v_pk_fma_f32 v[144:145], v[78:79], v[168:169], v[146:147]
	v_pk_fma_f32 v[146:147], v[76:77], v[168:169], v[148:149]
	v_pk_fma_f32 v[148:149], v[74:75], v[168:169], v[152:153]
	v_pk_fma_f32 v[152:153], v[72:73], v[168:169], v[154:155]
	v_pk_fma_f32 v[154:155], v[70:71], v[168:169], v[156:157]
	v_pk_fma_f32 v[156:157], v[68:69], v[168:169], v[158:159]
	v_pk_fma_f32 v[134:135], v[66:67], v[168:169], v[134:135]
	v_pk_fma_f32 v[158:159], v[64:65], v[168:169], v[160:161]
	v_pk_fma_f32 v[160:161], v[62:63], v[168:169], v[162:163]
	v_pk_fma_f32 v[162:163], v[60:61], v[168:169], v[164:165]
	v_pk_fma_f32 v[164:165], v[52:53], v[168:169], v[166:167]
	v_cndmask_b32_e64 v39, 0, v0, s[52:53]
	s_waitcnt vmcnt(24)
	v_lshlrev_b32_e32 v0, 16, v36
	v_pk_fma_f32 v[42:43], v[90:91], v[38:39], v[42:43]
	v_pk_fma_f32 v[46:47], v[88:89], v[38:39], v[46:47]
	v_pk_fma_f32 v[48:49], v[86:87], v[38:39], v[48:49]
	v_pk_fma_f32 v[136:137], v[84:85], v[38:39], v[136:137]
	v_pk_fma_f32 v[142:143], v[82:83], v[38:39], v[142:143]
	v_pk_fma_f32 v[144:145], v[80:81], v[38:39], v[144:145]
	v_pk_fma_f32 v[146:147], v[78:79], v[38:39], v[146:147]
	v_pk_fma_f32 v[148:149], v[76:77], v[38:39], v[148:149]
	v_pk_fma_f32 v[152:153], v[74:75], v[38:39], v[152:153]
	v_pk_fma_f32 v[154:155], v[72:73], v[38:39], v[154:155]
	v_pk_fma_f32 v[156:157], v[70:71], v[38:39], v[156:157]
	v_pk_fma_f32 v[134:135], v[68:69], v[38:39], v[134:135]
	v_pk_fma_f32 v[158:159], v[66:67], v[38:39], v[158:159]
	v_pk_fma_f32 v[160:161], v[64:65], v[38:39], v[160:161]
	v_pk_fma_f32 v[162:163], v[62:63], v[38:39], v[162:163]
	v_pk_fma_f32 v[38:39], v[60:61], v[38:39], v[164:165]
	v_cndmask_b32_e64 v164, 0, v0, s[44:45]
	v_and_b32_e32 v0, 0xffff0000, v36
	v_cndmask_b32_e64 v165, 0, v0, s[44:45]
	s_waitcnt vmcnt(23)
	v_lshlrev_b32_e32 v0, 16, v33
	v_cndmask_b32_e64 v32, 0, v0, s[38:39]
	v_and_b32_e32 v0, 0xffff0000, v33
	v_pk_fma_f32 v[42:43], v[92:93], v[164:165], v[42:43]
	v_pk_fma_f32 v[46:47], v[90:91], v[164:165], v[46:47]
	v_pk_fma_f32 v[48:49], v[88:89], v[164:165], v[48:49]
	v_pk_fma_f32 v[136:137], v[86:87], v[164:165], v[136:137]
	v_pk_fma_f32 v[142:143], v[84:85], v[164:165], v[142:143]
	v_pk_fma_f32 v[144:145], v[82:83], v[164:165], v[144:145]
	v_pk_fma_f32 v[146:147], v[80:81], v[164:165], v[146:147]
	v_pk_fma_f32 v[148:149], v[78:79], v[164:165], v[148:149]
	v_pk_fma_f32 v[152:153], v[76:77], v[164:165], v[152:153]
	v_pk_fma_f32 v[154:155], v[74:75], v[164:165], v[154:155]
	v_pk_fma_f32 v[156:157], v[72:73], v[164:165], v[156:157]
	v_pk_fma_f32 v[134:135], v[70:71], v[164:165], v[134:135]
	v_pk_fma_f32 v[158:159], v[68:69], v[164:165], v[158:159]
	v_pk_fma_f32 v[160:161], v[66:67], v[164:165], v[160:161]
	v_pk_fma_f32 v[162:163], v[64:65], v[164:165], v[162:163]
	v_pk_fma_f32 v[38:39], v[62:63], v[164:165], v[38:39]
	v_cndmask_b32_e64 v33, 0, v0, s[38:39]
	s_waitcnt vmcnt(22)
	v_lshlrev_b32_e32 v0, 16, v40
	v_pk_fma_f32 v[42:43], v[94:95], v[32:33], v[42:43]
	v_pk_fma_f32 v[46:47], v[92:93], v[32:33], v[46:47]
	v_pk_fma_f32 v[48:49], v[90:91], v[32:33], v[48:49]
	v_pk_fma_f32 v[136:137], v[88:89], v[32:33], v[136:137]
	v_pk_fma_f32 v[142:143], v[86:87], v[32:33], v[142:143]
	v_pk_fma_f32 v[144:145], v[84:85], v[32:33], v[144:145]
	v_pk_fma_f32 v[146:147], v[82:83], v[32:33], v[146:147]
	v_pk_fma_f32 v[148:149], v[80:81], v[32:33], v[148:149]
	v_pk_fma_f32 v[152:153], v[78:79], v[32:33], v[152:153]
	v_pk_fma_f32 v[154:155], v[76:77], v[32:33], v[154:155]
	v_pk_fma_f32 v[156:157], v[74:75], v[32:33], v[156:157]
	v_pk_fma_f32 v[134:135], v[72:73], v[32:33], v[134:135]
	v_pk_fma_f32 v[158:159], v[70:71], v[32:33], v[158:159]
	v_pk_fma_f32 v[160:161], v[68:69], v[32:33], v[160:161]
	v_pk_fma_f32 v[162:163], v[66:67], v[32:33], v[162:163]
	v_pk_fma_f32 v[32:33], v[64:65], v[32:33], v[38:39]
	v_cndmask_b32_e64 v38, 0, v0, s[24:25]
	v_and_b32_e32 v0, 0xffff0000, v40
	v_cndmask_b32_e64 v39, 0, v0, s[24:25]
	s_waitcnt vmcnt(21)
	v_lshlrev_b32_e32 v0, 16, v41
	v_pk_fma_f32 v[42:43], v[96:97], v[38:39], v[42:43]
	v_pk_fma_f32 v[46:47], v[94:95], v[38:39], v[46:47]
	v_pk_fma_f32 v[48:49], v[92:93], v[38:39], v[48:49]
	v_pk_fma_f32 v[136:137], v[90:91], v[38:39], v[136:137]
	v_pk_fma_f32 v[142:143], v[88:89], v[38:39], v[142:143]
	v_pk_fma_f32 v[144:145], v[86:87], v[38:39], v[144:145]
	v_pk_fma_f32 v[146:147], v[84:85], v[38:39], v[146:147]
	v_pk_fma_f32 v[148:149], v[82:83], v[38:39], v[148:149]
	v_pk_fma_f32 v[152:153], v[80:81], v[38:39], v[152:153]
	v_pk_fma_f32 v[154:155], v[78:79], v[38:39], v[154:155]
	v_pk_fma_f32 v[156:157], v[76:77], v[38:39], v[156:157]
	v_pk_fma_f32 v[134:135], v[74:75], v[38:39], v[134:135]
	v_pk_fma_f32 v[158:159], v[72:73], v[38:39], v[158:159]
	v_pk_fma_f32 v[160:161], v[70:71], v[38:39], v[160:161]
	v_pk_fma_f32 v[162:163], v[68:69], v[38:39], v[162:163]
	v_pk_fma_f32 v[32:33], v[66:67], v[38:39], v[32:33]
	v_cndmask_b32_e64 v38, 0, v0, s[54:55]
	v_and_b32_e32 v0, 0xffff0000, v41
	v_cndmask_b32_e64 v39, 0, v0, s[54:55]
	s_waitcnt vmcnt(20)
	v_lshlrev_b32_e32 v0, 16, v37
	v_cndmask_b32_e64 v36, 0, v0, s[48:49]
	v_and_b32_e32 v0, 0xffff0000, v37
	v_pk_fma_f32 v[40:41], v[98:99], v[38:39], v[42:43]
	v_pk_fma_f32 v[42:43], v[96:97], v[38:39], v[46:47]
	v_pk_fma_f32 v[46:47], v[94:95], v[38:39], v[48:49]
	v_pk_fma_f32 v[48:49], v[92:93], v[38:39], v[136:137]
	v_pk_fma_f32 v[136:137], v[90:91], v[38:39], v[142:143]
	v_pk_fma_f32 v[142:143], v[88:89], v[38:39], v[144:145]
	v_pk_fma_f32 v[144:145], v[86:87], v[38:39], v[146:147]
	v_pk_fma_f32 v[146:147], v[84:85], v[38:39], v[148:149]
	v_pk_fma_f32 v[148:149], v[82:83], v[38:39], v[152:153]
	v_pk_fma_f32 v[152:153], v[80:81], v[38:39], v[154:155]
	v_pk_fma_f32 v[154:155], v[78:79], v[38:39], v[156:157]
	v_pk_fma_f32 v[134:135], v[76:77], v[38:39], v[134:135]
	v_pk_fma_f32 v[156:157], v[74:75], v[38:39], v[158:159]
	v_pk_fma_f32 v[158:159], v[72:73], v[38:39], v[160:161]
	v_pk_fma_f32 v[160:161], v[70:71], v[38:39], v[162:163]
	v_pk_fma_f32 v[32:33], v[68:69], v[38:39], v[32:33]
	v_cndmask_b32_e64 v37, 0, v0, s[48:49]
	s_waitcnt vmcnt(19)
	v_lshlrev_b32_e32 v0, 16, v35
	v_pk_fma_f32 v[38:39], v[100:101], v[36:37], v[40:41]
	v_pk_fma_f32 v[40:41], v[98:99], v[36:37], v[42:43]
	v_pk_fma_f32 v[42:43], v[96:97], v[36:37], v[46:47]
	v_pk_fma_f32 v[46:47], v[94:95], v[36:37], v[48:49]
	v_pk_fma_f32 v[48:49], v[92:93], v[36:37], v[136:137]
	v_pk_fma_f32 v[136:137], v[90:91], v[36:37], v[142:143]
	v_pk_fma_f32 v[142:143], v[88:89], v[36:37], v[144:145]
	v_pk_fma_f32 v[144:145], v[86:87], v[36:37], v[146:147]
	v_pk_fma_f32 v[146:147], v[84:85], v[36:37], v[148:149]
	v_pk_fma_f32 v[148:149], v[82:83], v[36:37], v[152:153]
	v_pk_fma_f32 v[152:153], v[80:81], v[36:37], v[154:155]
	v_pk_fma_f32 v[134:135], v[78:79], v[36:37], v[134:135]
	v_pk_fma_f32 v[154:155], v[76:77], v[36:37], v[156:157]
	v_pk_fma_f32 v[156:157], v[74:75], v[36:37], v[158:159]
	v_pk_fma_f32 v[158:159], v[72:73], v[36:37], v[160:161]
	v_pk_fma_f32 v[32:33], v[70:71], v[36:37], v[32:33]
	v_cndmask_b32_e64 v36, 0, v0, s[42:43]
	v_and_b32_e32 v0, 0xffff0000, v35
	v_cndmask_b32_e64 v37, 0, v0, s[42:43]
	s_waitcnt vmcnt(18)
	v_lshlrev_b32_e32 v0, 16, v30
	v_pk_fma_f32 v[38:39], v[102:103], v[36:37], v[38:39]
	v_pk_fma_f32 v[40:41], v[100:101], v[36:37], v[40:41]
	v_pk_fma_f32 v[42:43], v[98:99], v[36:37], v[42:43]
	v_pk_fma_f32 v[46:47], v[96:97], v[36:37], v[46:47]
	v_pk_fma_f32 v[48:49], v[94:95], v[36:37], v[48:49]
	v_pk_fma_f32 v[136:137], v[92:93], v[36:37], v[136:137]
	v_pk_fma_f32 v[142:143], v[90:91], v[36:37], v[142:143]
	v_pk_fma_f32 v[144:145], v[88:89], v[36:37], v[144:145]
	v_pk_fma_f32 v[146:147], v[86:87], v[36:37], v[146:147]
	v_pk_fma_f32 v[148:149], v[84:85], v[36:37], v[148:149]
	v_pk_fma_f32 v[152:153], v[82:83], v[36:37], v[152:153]
	v_pk_fma_f32 v[134:135], v[80:81], v[36:37], v[134:135]
	v_pk_fma_f32 v[154:155], v[78:79], v[36:37], v[154:155]
	v_pk_fma_f32 v[156:157], v[76:77], v[36:37], v[156:157]
	v_pk_fma_f32 v[158:159], v[74:75], v[36:37], v[158:159]
	v_pk_fma_f32 v[32:33], v[72:73], v[36:37], v[32:33]
	v_cndmask_b32_e64 v36, 0, v0, s[34:35]
	v_and_b32_e32 v0, 0xffff0000, v30
	v_cndmask_b32_e64 v37, 0, v0, s[34:35]
	s_waitcnt vmcnt(17)
	v_lshlrev_b32_e32 v0, 16, v22
	v_pk_fma_f32 v[38:39], v[104:105], v[36:37], v[38:39]
	v_pk_fma_f32 v[40:41], v[102:103], v[36:37], v[40:41]
	v_pk_fma_f32 v[42:43], v[100:101], v[36:37], v[42:43]
	v_pk_fma_f32 v[46:47], v[98:99], v[36:37], v[46:47]
	v_pk_fma_f32 v[48:49], v[96:97], v[36:37], v[48:49]
	v_pk_fma_f32 v[136:137], v[94:95], v[36:37], v[136:137]
	v_pk_fma_f32 v[142:143], v[92:93], v[36:37], v[142:143]
	v_pk_fma_f32 v[144:145], v[90:91], v[36:37], v[144:145]
	v_pk_fma_f32 v[146:147], v[88:89], v[36:37], v[146:147]
	v_pk_fma_f32 v[148:149], v[86:87], v[36:37], v[148:149]
	v_pk_fma_f32 v[152:153], v[84:85], v[36:37], v[152:153]
	v_pk_fma_f32 v[134:135], v[82:83], v[36:37], v[134:135]
	v_pk_fma_f32 v[154:155], v[80:81], v[36:37], v[154:155]
	v_pk_fma_f32 v[156:157], v[78:79], v[36:37], v[156:157]
	v_pk_fma_f32 v[158:159], v[76:77], v[36:37], v[158:159]
	v_pk_fma_f32 v[32:33], v[74:75], v[36:37], v[32:33]
	v_cndmask_b32_e64 v36, 0, v0, s[14:15]
	v_and_b32_e32 v0, 0xffff0000, v22
	v_cndmask_b32_e64 v37, 0, v0, s[14:15]
	s_waitcnt vmcnt(16)
	v_lshlrev_b32_e32 v0, 16, v20
	v_pk_fma_f32 v[38:39], v[106:107], v[36:37], v[38:39]
	v_pk_fma_f32 v[40:41], v[104:105], v[36:37], v[40:41]
	v_pk_fma_f32 v[42:43], v[102:103], v[36:37], v[42:43]
	v_pk_fma_f32 v[46:47], v[100:101], v[36:37], v[46:47]
	v_pk_fma_f32 v[48:49], v[98:99], v[36:37], v[48:49]
	v_pk_fma_f32 v[136:137], v[96:97], v[36:37], v[136:137]
	v_pk_fma_f32 v[142:143], v[94:95], v[36:37], v[142:143]
	v_pk_fma_f32 v[144:145], v[92:93], v[36:37], v[144:145]
	v_pk_fma_f32 v[146:147], v[90:91], v[36:37], v[146:147]
	v_pk_fma_f32 v[148:149], v[88:89], v[36:37], v[148:149]
	v_pk_fma_f32 v[152:153], v[86:87], v[36:37], v[152:153]
	v_pk_fma_f32 v[134:135], v[84:85], v[36:37], v[134:135]
	v_pk_fma_f32 v[154:155], v[82:83], v[36:37], v[154:155]
	v_pk_fma_f32 v[156:157], v[80:81], v[36:37], v[156:157]
	v_pk_fma_f32 v[158:159], v[78:79], v[36:37], v[158:159]
	v_pk_fma_f32 v[32:33], v[76:77], v[36:37], v[32:33]
	v_cndmask_b32_e64 v36, 0, v0, s[10:11]
	v_and_b32_e32 v0, 0xffff0000, v20
	v_cndmask_b32_e64 v37, 0, v0, s[10:11]
	s_waitcnt vmcnt(15)
	v_lshlrev_b32_e32 v0, 16, v19
	v_cndmask_b32_e64 v18, 0, v0, s[8:9]
	v_and_b32_e32 v0, 0xffff0000, v19
	v_pk_fma_f32 v[20:21], v[108:109], v[36:37], v[38:39]
	v_pk_fma_f32 v[38:39], v[106:107], v[36:37], v[40:41]
	v_pk_fma_f32 v[40:41], v[104:105], v[36:37], v[42:43]
	v_pk_fma_f32 v[42:43], v[102:103], v[36:37], v[46:47]
	v_pk_fma_f32 v[46:47], v[100:101], v[36:37], v[48:49]
	v_pk_fma_f32 v[48:49], v[98:99], v[36:37], v[136:137]
	v_pk_fma_f32 v[136:137], v[96:97], v[36:37], v[142:143]
	v_pk_fma_f32 v[142:143], v[94:95], v[36:37], v[144:145]
	v_pk_fma_f32 v[144:145], v[92:93], v[36:37], v[146:147]
	v_pk_fma_f32 v[146:147], v[90:91], v[36:37], v[148:149]
	v_pk_fma_f32 v[148:149], v[88:89], v[36:37], v[152:153]
	v_pk_fma_f32 v[134:135], v[86:87], v[36:37], v[134:135]
	v_pk_fma_f32 v[152:153], v[84:85], v[36:37], v[154:155]
	v_pk_fma_f32 v[154:155], v[82:83], v[36:37], v[156:157]
	v_pk_fma_f32 v[156:157], v[80:81], v[36:37], v[158:159]
	v_pk_fma_f32 v[32:33], v[78:79], v[36:37], v[32:33]
	v_cndmask_b32_e64 v19, 0, v0, s[8:9]
	s_waitcnt vmcnt(14)
	v_lshlrev_b32_e32 v0, 16, v27
	v_pk_fma_f32 v[20:21], v[110:111], v[18:19], v[20:21]
	v_pk_fma_f32 v[36:37], v[108:109], v[18:19], v[38:39]
	v_pk_fma_f32 v[38:39], v[106:107], v[18:19], v[40:41]
	v_pk_fma_f32 v[40:41], v[104:105], v[18:19], v[42:43]
	v_pk_fma_f32 v[42:43], v[102:103], v[18:19], v[46:47]
	v_pk_fma_f32 v[46:47], v[100:101], v[18:19], v[48:49]
	v_pk_fma_f32 v[48:49], v[98:99], v[18:19], v[136:137]
	v_pk_fma_f32 v[136:137], v[96:97], v[18:19], v[142:143]
	v_pk_fma_f32 v[142:143], v[94:95], v[18:19], v[144:145]
	v_pk_fma_f32 v[144:145], v[92:93], v[18:19], v[146:147]
	v_pk_fma_f32 v[146:147], v[90:91], v[18:19], v[148:149]
	v_pk_fma_f32 v[134:135], v[88:89], v[18:19], v[134:135]
	v_pk_fma_f32 v[148:149], v[86:87], v[18:19], v[152:153]
	v_pk_fma_f32 v[152:153], v[84:85], v[18:19], v[154:155]
	v_pk_fma_f32 v[154:155], v[82:83], v[18:19], v[156:157]
	v_pk_fma_f32 v[18:19], v[80:81], v[18:19], v[32:33]
	v_cndmask_b32_e64 v32, 0, v0, s[4:5]
	v_and_b32_e32 v0, 0xffff0000, v27
	v_cndmask_b32_e64 v33, 0, v0, s[4:5]
	s_waitcnt vmcnt(13)
	v_lshlrev_b32_e32 v0, 16, v31
	v_cndmask_b32_e64 v30, 0, v0, s[26:27]
	v_and_b32_e32 v0, 0xffff0000, v31
	v_pk_fma_f32 v[38:39], v[108:109], v[32:33], v[38:39]
	v_pk_fma_f32 v[40:41], v[106:107], v[32:33], v[40:41]
	v_pk_fma_f32 v[42:43], v[104:105], v[32:33], v[42:43]
	v_pk_fma_f32 v[46:47], v[102:103], v[32:33], v[46:47]
	v_pk_fma_f32 v[48:49], v[100:101], v[32:33], v[48:49]
	v_pk_fma_f32 v[136:137], v[98:99], v[32:33], v[136:137]
	v_pk_fma_f32 v[142:143], v[96:97], v[32:33], v[142:143]
	v_pk_fma_f32 v[144:145], v[94:95], v[32:33], v[144:145]
	v_pk_fma_f32 v[146:147], v[92:93], v[32:33], v[146:147]
	v_pk_fma_f32 v[134:135], v[90:91], v[32:33], v[134:135]
	v_pk_fma_f32 v[148:149], v[88:89], v[32:33], v[148:149]
	v_pk_fma_f32 v[152:153], v[86:87], v[32:33], v[152:153]
	v_pk_fma_f32 v[154:155], v[84:85], v[32:33], v[154:155]
	v_pk_fma_f32 v[18:19], v[82:83], v[32:33], v[18:19]
	v_cndmask_b32_e64 v31, 0, v0, s[26:27]
	s_waitcnt vmcnt(12)
	v_lshlrev_b32_e32 v0, 16, v25
	v_pk_fma_f32 v[36:37], v[110:111], v[32:33], v[36:37]
	v_pk_fma_f32 v[32:33], v[110:111], v[30:31], v[38:39]
	v_pk_fma_f32 v[38:39], v[108:109], v[30:31], v[40:41]
	v_pk_fma_f32 v[40:41], v[106:107], v[30:31], v[42:43]
	v_pk_fma_f32 v[42:43], v[104:105], v[30:31], v[46:47]
	v_pk_fma_f32 v[46:47], v[102:103], v[30:31], v[48:49]
	v_pk_fma_f32 v[48:49], v[100:101], v[30:31], v[136:137]
	v_pk_fma_f32 v[136:137], v[98:99], v[30:31], v[142:143]
	v_pk_fma_f32 v[142:143], v[96:97], v[30:31], v[144:145]
	v_pk_fma_f32 v[144:145], v[94:95], v[30:31], v[146:147]
	v_pk_fma_f32 v[134:135], v[92:93], v[30:31], v[134:135]
	v_pk_fma_f32 v[146:147], v[90:91], v[30:31], v[148:149]
	v_pk_fma_f32 v[148:149], v[88:89], v[30:31], v[152:153]
	v_pk_fma_f32 v[152:153], v[86:87], v[30:31], v[154:155]
	v_pk_fma_f32 v[18:19], v[84:85], v[30:31], v[18:19]
	v_cndmask_b32_e64 v30, 0, v0, s[20:21]
	v_and_b32_e32 v0, 0xffff0000, v25
	v_cndmask_b32_e64 v31, 0, v0, s[20:21]
	s_waitcnt vmcnt(11)
	v_lshlrev_b32_e32 v0, 16, v23
	v_cndmask_b32_e64 v22, 0, v0, s[16:17]
	v_and_b32_e32 v0, 0xffff0000, v23
	v_pk_fma_f32 v[40:41], v[108:109], v[30:31], v[40:41]
	v_pk_fma_f32 v[42:43], v[106:107], v[30:31], v[42:43]
	v_pk_fma_f32 v[46:47], v[104:105], v[30:31], v[46:47]
	v_pk_fma_f32 v[48:49], v[102:103], v[30:31], v[48:49]
	v_pk_fma_f32 v[136:137], v[100:101], v[30:31], v[136:137]
	v_pk_fma_f32 v[142:143], v[98:99], v[30:31], v[142:143]
	v_pk_fma_f32 v[144:145], v[96:97], v[30:31], v[144:145]
	v_pk_fma_f32 v[134:135], v[94:95], v[30:31], v[134:135]
	v_pk_fma_f32 v[146:147], v[92:93], v[30:31], v[146:147]
	v_pk_fma_f32 v[148:149], v[90:91], v[30:31], v[148:149]
	v_pk_fma_f32 v[152:153], v[88:89], v[30:31], v[152:153]
	v_pk_fma_f32 v[18:19], v[86:87], v[30:31], v[18:19]
	v_cndmask_b32_e64 v23, 0, v0, s[16:17]
	s_waitcnt vmcnt(10)
	v_lshlrev_b32_e32 v0, 16, v24
	v_pk_fma_f32 v[38:39], v[110:111], v[30:31], v[38:39]
	v_pk_fma_f32 v[30:31], v[110:111], v[22:23], v[40:41]
	v_pk_fma_f32 v[40:41], v[108:109], v[22:23], v[42:43]
	v_pk_fma_f32 v[42:43], v[106:107], v[22:23], v[46:47]
	v_pk_fma_f32 v[46:47], v[104:105], v[22:23], v[48:49]
	v_pk_fma_f32 v[48:49], v[102:103], v[22:23], v[136:137]
	v_pk_fma_f32 v[136:137], v[100:101], v[22:23], v[142:143]
	v_pk_fma_f32 v[142:143], v[98:99], v[22:23], v[144:145]
	v_pk_fma_f32 v[134:135], v[96:97], v[22:23], v[134:135]
	v_pk_fma_f32 v[144:145], v[94:95], v[22:23], v[146:147]
	v_pk_fma_f32 v[146:147], v[92:93], v[22:23], v[148:149]
	v_pk_fma_f32 v[148:149], v[90:91], v[22:23], v[152:153]
	v_pk_fma_f32 v[18:19], v[88:89], v[22:23], v[18:19]
	v_cndmask_b32_e64 v22, 0, v0, s[18:19]
	v_and_b32_e32 v0, 0xffff0000, v24
	v_cndmask_b32_e64 v23, 0, v0, s[18:19]
	s_waitcnt vmcnt(9)
	v_lshlrev_b32_e32 v0, 16, v26
	v_pk_fma_f32 v[24:25], v[110:111], v[22:23], v[40:41]
	v_pk_fma_f32 v[40:41], v[108:109], v[22:23], v[42:43]
	v_pk_fma_f32 v[42:43], v[106:107], v[22:23], v[46:47]
	v_pk_fma_f32 v[46:47], v[104:105], v[22:23], v[48:49]
	v_pk_fma_f32 v[48:49], v[102:103], v[22:23], v[136:137]
	v_pk_fma_f32 v[136:137], v[100:101], v[22:23], v[142:143]
	v_pk_fma_f32 v[134:135], v[98:99], v[22:23], v[134:135]
	v_pk_fma_f32 v[142:143], v[96:97], v[22:23], v[144:145]
	v_pk_fma_f32 v[144:145], v[94:95], v[22:23], v[146:147]
	v_pk_fma_f32 v[146:147], v[92:93], v[22:23], v[148:149]
	v_pk_fma_f32 v[18:19], v[90:91], v[22:23], v[18:19]
	v_cndmask_b32_e64 v22, 0, v0, s[22:23]
	v_and_b32_e32 v0, 0xffff0000, v26
	v_cndmask_b32_e64 v23, 0, v0, s[22:23]
	s_waitcnt vmcnt(8)
	v_lshlrev_b32_e32 v0, 16, v28
	v_pk_fma_f32 v[26:27], v[110:111], v[22:23], v[40:41]
	v_pk_fma_f32 v[40:41], v[108:109], v[22:23], v[42:43]
	v_pk_fma_f32 v[42:43], v[106:107], v[22:23], v[46:47]
	v_pk_fma_f32 v[46:47], v[104:105], v[22:23], v[48:49]
	v_pk_fma_f32 v[48:49], v[102:103], v[22:23], v[136:137]
	v_pk_fma_f32 v[134:135], v[100:101], v[22:23], v[134:135]
	v_pk_fma_f32 v[136:137], v[98:99], v[22:23], v[142:143]
	v_pk_fma_f32 v[142:143], v[96:97], v[22:23], v[144:145]
	v_pk_fma_f32 v[144:145], v[94:95], v[22:23], v[146:147]
	v_pk_fma_f32 v[18:19], v[92:93], v[22:23], v[18:19]
	v_cndmask_b32_e64 v22, 0, v0, s[28:29]
	v_and_b32_e32 v0, 0xffff0000, v28
	v_cndmask_b32_e64 v23, 0, v0, s[28:29]
	s_waitcnt vmcnt(7)
	v_lshlrev_b32_e32 v0, 16, v34
	v_pk_fma_f32 v[28:29], v[110:111], v[22:23], v[40:41]
	v_pk_fma_f32 v[40:41], v[108:109], v[22:23], v[42:43]
	v_pk_fma_f32 v[42:43], v[106:107], v[22:23], v[46:47]
	v_pk_fma_f32 v[46:47], v[104:105], v[22:23], v[48:49]
	v_pk_fma_f32 v[48:49], v[102:103], v[22:23], v[134:135]
	v_pk_fma_f32 v[134:135], v[100:101], v[22:23], v[136:137]
	v_pk_fma_f32 v[136:137], v[98:99], v[22:23], v[142:143]
	v_pk_fma_f32 v[142:143], v[96:97], v[22:23], v[144:145]
	v_pk_fma_f32 v[18:19], v[94:95], v[22:23], v[18:19]
	v_cndmask_b32_e64 v22, 0, v0, s[40:41]
	v_and_b32_e32 v0, 0xffff0000, v34
	v_cndmask_b32_e64 v23, 0, v0, s[40:41]
	s_waitcnt vmcnt(6)
	v_lshlrev_b32_e32 v0, 16, v45
	v_pk_fma_f32 v[34:35], v[110:111], v[22:23], v[40:41]
	v_pk_fma_f32 v[40:41], v[108:109], v[22:23], v[42:43]
	v_pk_fma_f32 v[42:43], v[106:107], v[22:23], v[46:47]
	v_pk_fma_f32 v[46:47], v[104:105], v[22:23], v[48:49]
	v_pk_fma_f32 v[48:49], v[102:103], v[22:23], v[134:135]
	v_pk_fma_f32 v[134:135], v[100:101], v[22:23], v[136:137]
	v_pk_fma_f32 v[136:137], v[98:99], v[22:23], v[142:143]
	v_pk_fma_f32 v[18:19], v[96:97], v[22:23], v[18:19]
	v_cndmask_b32_e64 v22, 0, v0, s[46:47]
	v_and_b32_e32 v0, 0xffff0000, v45
	v_cndmask_b32_e64 v23, 0, v0, s[46:47]
	s_waitcnt vmcnt(5)
	v_lshlrev_b32_e32 v0, 16, v118
	v_pk_fma_f32 v[40:41], v[110:111], v[22:23], v[40:41]
	v_pk_fma_f32 v[42:43], v[108:109], v[22:23], v[42:43]
	v_pk_fma_f32 v[44:45], v[106:107], v[22:23], v[46:47]
	v_pk_fma_f32 v[46:47], v[104:105], v[22:23], v[48:49]
	v_pk_fma_f32 v[48:49], v[102:103], v[22:23], v[134:135]
	v_pk_fma_f32 v[134:135], v[100:101], v[22:23], v[136:137]
	v_pk_fma_f32 v[18:19], v[98:99], v[22:23], v[18:19]
	v_cndmask_b32_e64 v22, 0, v0, s[66:67]
	v_and_b32_e32 v0, 0xffff0000, v118
	v_cndmask_b32_e64 v23, 0, v0, s[66:67]
	s_waitcnt vmcnt(4)
	v_lshlrev_b32_e32 v0, 16, v120
	v_pk_fma_f32 v[42:43], v[110:111], v[22:23], v[42:43]
	v_pk_fma_f32 v[44:45], v[108:109], v[22:23], v[44:45]
	v_pk_fma_f32 v[46:47], v[106:107], v[22:23], v[46:47]
	v_pk_fma_f32 v[48:49], v[104:105], v[22:23], v[48:49]
	v_pk_fma_f32 v[118:119], v[102:103], v[22:23], v[134:135]
	v_pk_fma_f32 v[18:19], v[100:101], v[22:23], v[18:19]
	v_cndmask_b32_e64 v22, 0, v0, s[68:69]
	v_and_b32_e32 v0, 0xffff0000, v120
	v_cndmask_b32_e64 v23, 0, v0, s[68:69]
	s_waitcnt vmcnt(3)
	v_lshlrev_b32_e32 v0, 16, v133
	v_pk_fma_f32 v[44:45], v[110:111], v[22:23], v[44:45]
	v_pk_fma_f32 v[46:47], v[108:109], v[22:23], v[46:47]
	v_pk_fma_f32 v[48:49], v[106:107], v[22:23], v[48:49]
	v_pk_fma_f32 v[118:119], v[104:105], v[22:23], v[118:119]
	v_pk_fma_f32 v[18:19], v[102:103], v[22:23], v[18:19]
	v_cndmask_b32_e64 v22, 0, v0, s[72:73]
	v_and_b32_e32 v0, 0xffff0000, v133
	v_cndmask_b32_e64 v23, 0, v0, s[72:73]
	s_waitcnt vmcnt(2)
	v_lshlrev_b32_e32 v0, 16, v139
	v_pk_fma_f32 v[46:47], v[110:111], v[22:23], v[46:47]
	v_pk_fma_f32 v[48:49], v[108:109], v[22:23], v[48:49]
	v_pk_fma_f32 v[118:119], v[106:107], v[22:23], v[118:119]
	v_pk_fma_f32 v[18:19], v[104:105], v[22:23], v[18:19]
	v_cndmask_b32_e64 v22, 0, v0, s[80:81]
	v_and_b32_e32 v0, 0xffff0000, v139
	v_cndmask_b32_e64 v23, 0, v0, s[80:81]
	s_waitcnt vmcnt(1)
	v_lshlrev_b32_e32 v0, 16, v140
	v_pk_fma_f32 v[48:49], v[110:111], v[22:23], v[48:49]
	v_pk_fma_f32 v[118:119], v[108:109], v[22:23], v[118:119]
	v_pk_fma_f32 v[18:19], v[106:107], v[22:23], v[18:19]
	v_cndmask_b32_e64 v22, 0, v0, s[82:83]
	v_and_b32_e32 v0, 0xffff0000, v140
	v_cndmask_b32_e64 v23, 0, v0, s[82:83]
	s_waitcnt vmcnt(0)
	v_lshlrev_b32_e32 v0, 16, v141
	v_pk_fma_f32 v[118:119], v[110:111], v[22:23], v[118:119]
	v_pk_fma_f32 v[18:19], v[108:109], v[22:23], v[18:19]
	v_cndmask_b32_e64 v22, 0, v0, s[84:85]
	v_and_b32_e32 v0, 0xffff0000, v141
	v_cndmask_b32_e64 v23, 0, v0, s[84:85]
	v_pk_fma_f32 v[18:19], v[110:111], v[22:23], v[18:19]
	ds_write2st64_b64 v122, v[20:21], v[36:37] offset1:8
	ds_write2st64_b64 v122, v[32:33], v[38:39] offset0:16 offset1:24
	ds_write2st64_b64 v122, v[30:31], v[24:25] offset0:32 offset1:40
	ds_write2st64_b64 v122, v[26:27], v[28:29] offset0:48 offset1:56
	ds_write2st64_b64 v122, v[34:35], v[40:41] offset0:64 offset1:72
	ds_write2st64_b64 v122, v[42:43], v[44:45] offset0:80 offset1:88
	ds_write2st64_b64 v122, v[46:47], v[48:49] offset0:96 offset1:104
	ds_write2st64_b64 v122, v[118:119], v[18:19] offset0:112 offset1:120
	s_waitcnt lgkmcnt(0)
	s_barrier
	ds_read_b128 v[46:49], v131
	ds_read_b128 v[42:45], v131 offset:1024
	ds_read_b128 v[38:41], v131 offset:2048
	ds_read_b128 v[34:37], v131 offset:3072
	ds_read_b128 v[30:33], v132
	ds_read_b128 v[26:29], v132 offset:1024
	s_waitcnt lgkmcnt(5)
	v_mov_b32_e32 v18, v47
	v_mov_b32_e32 v19, v48
	v_mov_b32_e32 v20, v46
	v_mov_b32_e32 v21, v49
	v_pk_add_f32 v[18:19], v[18:19], v[20:21]
	s_waitcnt lgkmcnt(4)
	v_mov_b32_e32 v20, v43
	v_mov_b32_e32 v21, v44
	v_mov_b32_e32 v22, v42
	v_mov_b32_e32 v23, v45
	v_pk_add_f32 v[20:21], v[20:21], v[22:23]
	v_add_f32_e32 v0, v18, v19
	v_pk_add_f32 v[20:21], v[20:21], v[20:21] op_sel:[0,1] op_sel_hi:[1,0]
	v_add_f32_e32 v18, 0, v0
	s_waitcnt lgkmcnt(3)
	v_add_f32_e32 v22, v38, v39
	v_add_f32_e32 v24, v40, v41
	s_waitcnt lgkmcnt(2)
	v_mov_b32_e32 v19, v34
	v_mov_b32_e32 v21, v35
	v_mov_b32_e32 v23, v36
	v_mov_b32_e32 v25, v37
	v_pk_add_f32 v[18:19], v[18:19], v[20:21]
	v_pk_add_f32 v[20:21], v[22:23], v[24:25]
	s_waitcnt lgkmcnt(0)
	v_mov_b32_e32 v136, v27
	v_pk_add_f32 v[18:19], v[18:19], v[20:21]
	v_mov_b32_e32 v137, v28
	v_add_f32_e32 v0, v18, v19
	v_mov_b32_e32 v204, v0
	s_nop 1
	v_add_f32_dpp v204, v204, v204 quad_perm:[1,0,3,2] row_mask:0xf bank_mask:0xf
	s_nop 1
	v_add_f32_dpp v204, v204, v204 quad_perm:[2,3,0,1] row_mask:0xf bank_mask:0xf
	s_nop 1
	v_add_f32_dpp v204, v204, v204 row_ror:4 row_mask:0xf bank_mask:0xf
	s_nop 1
	v_add_f32_dpp v204, v204, v204 row_ror:8 row_mask:0xf bank_mask:0xf
	s_nop 1
	v_add_f32_dpp v204, v204, v204 row_bcast:15 row_mask:0xa bank_mask:0xf
	s_nop 1
	v_add_f32_dpp v204, v204, v204 row_bcast:31 row_mask:0xc bank_mask:0xf
	s_nop 1
	v_readlane_b32 s98, v204, 63
	v_mov_b32_e32 v138, v26
	v_mov_b32_e32 v139, v29
	v_pk_add_f32 v[136:137], v[136:137], v[138:139]
	s_mov_b32 s0, 0x3a800000
	v_pk_add_f32 v[136:137], v[136:137], v[136:137] op_sel:[0,1] op_sel_hi:[1,0]
	s_mov_b32 s50, 0x800000
	s_add_i32 s94, s94, s96
	s_mov_b32 s70, s96
	s_mov_b32 s84, s97
	s_waitcnt lgkmcnt(0)
	s_nop 1
	v_mov_b32_e32 v133, s98
	v_fmamk_f32 v121, v133, 0xba800000, v47
	v_fmamk_f32 v120, v133, 0xba800000, v46
	v_fmamk_f32 v49, v133, 0xba800000, v49
	v_fmac_f32_e32 v48, 0xba800000, v133
	v_pk_mul_f32 v[18:19], v[48:49], v[48:49]
	v_pk_mul_f32 v[20:21], v[120:121], v[120:121]
	v_fmamk_f32 v47, v133, 0xba800000, v43
	v_pk_mov_b32 v[22:23], v[20:21], v[18:19] op_sel:[1,0]
	v_mov_b32_e32 v21, v19
	v_pk_add_f32 v[18:19], v[22:23], v[20:21]
	v_mov_b32_e32 v20, v30
	v_pk_add_f32 v[134:135], v[18:19], v[18:19] op_sel_hi:[0,1]
	v_mov_b32_e32 v18, v31
	v_mov_b32_e32 v19, v32
	v_mov_b32_e32 v21, v33
	v_pk_add_f32 v[18:19], v[18:19], v[20:21]
	ds_read_b128 v[22:25], v132 offset:2048
	v_add_f32_e32 v0, v18, v19
	ds_read_b128 v[18:21], v132 offset:3072
	v_add_f32_e32 v118, 0, v0
	v_fmamk_f32 v46, v133, 0xba800000, v42
	s_waitcnt lgkmcnt(1)
	v_add_f32_e32 v138, v22, v23
	v_add_f32_e32 v140, v24, v25
	s_waitcnt lgkmcnt(0)
	v_mov_b32_e32 v119, v18
	v_mov_b32_e32 v137, v19
	v_mov_b32_e32 v139, v20
	v_mov_b32_e32 v141, v21
	v_pk_add_f32 v[118:119], v[118:119], v[136:137]
	v_pk_add_f32 v[136:137], v[138:139], v[140:141]
	v_fmamk_f32 v45, v133, 0xba800000, v45
	v_pk_add_f32 v[118:119], v[118:119], v[136:137]
	v_fmac_f32_e32 v44, 0xba800000, v133
	v_add_f32_e32 v0, v118, v119
	v_mov_b32_e32 v204, v0
	s_nop 1
	v_add_f32_dpp v204, v204, v204 quad_perm:[1,0,3,2] row_mask:0xf bank_mask:0xf
	s_nop 1
	v_add_f32_dpp v204, v204, v204 quad_perm:[2,3,0,1] row_mask:0xf bank_mask:0xf
	s_nop 1
	v_add_f32_dpp v204, v204, v204 row_ror:4 row_mask:0xf bank_mask:0xf
	s_nop 1
	v_add_f32_dpp v204, v204, v204 row_ror:8 row_mask:0xf bank_mask:0xf
	s_nop 1
	v_add_f32_dpp v204, v204, v204 row_bcast:15 row_mask:0xa bank_mask:0xf
	s_nop 1
	v_add_f32_dpp v204, v204, v204 row_bcast:31 row_mask:0xc bank_mask:0xf
	s_nop 1
	v_readlane_b32 s98, v204, 63
	v_pk_mul_f32 v[42:43], v[44:45], v[44:45]
	v_pk_mul_f32 v[118:119], v[46:47], v[46:47]
	v_fmac_f32_e32 v40, 0xba800000, v133
	v_pk_mov_b32 v[136:137], v[118:119], v[42:43] op_sel:[1,0]
	v_mov_b32_e32 v119, v43
	v_pk_add_f32 v[42:43], v[136:137], v[118:119]
	v_fmamk_f32 v118, v133, 0xba800000, v38
	v_pk_add_f32 v[42:43], v[42:43], v[42:43] op_sel_hi:[0,1]
	v_fmamk_f32 v119, v133, 0xba800000, v39
	v_mul_f32_e32 v0, v118, v118
	v_pk_fma_f32 v[38:39], v[118:119], v[118:119], v[0:1] op_sel_hi:[1,1,0]
	v_fmamk_f32 v41, v133, 0xba800000, v41
	v_mul_f32_e32 v0, v40, v40
	v_pk_fma_f32 v[136:137], v[40:41], v[40:41], v[0:1] op_sel_hi:[1,1,0]
	v_fmamk_f32 v37, v133, 0xba800000, v37
	v_fmamk_f32 v36, v133, 0xba800000, v36
	v_fmamk_f32 v35, v133, 0xba800000, v35
	v_fmac_f32_e32 v34, 0xba800000, v133
	v_mul_f32_e32 v38, v34, v34
	v_mul_f32_e32 v136, v35, v35
	v_mul_f32_e32 v134, v36, v36
	v_mul_f32_e32 v42, v37, v37
	v_pk_add_f32 v[38:39], v[38:39], v[136:137]
	v_pk_add_f32 v[42:43], v[134:135], v[42:43]
	s_waitcnt lgkmcnt(0)
	s_nop 1
	v_mov_b32_e32 v133, s98
	v_fmamk_f32 v31, v133, 0xba800000, v31
	v_fmamk_f32 v30, v133, 0xba800000, v30
	v_fmamk_f32 v33, v133, 0xba800000, v33
	v_fmac_f32_e32 v32, 0xba800000, v133
	v_pk_add_f32 v[38:39], v[38:39], v[42:43]
	v_pk_mul_f32 v[42:43], v[32:33], v[32:33]
	v_pk_mul_f32 v[134:135], v[30:31], v[30:31]
	v_fmamk_f32 v27, v133, 0xba800000, v27
	v_pk_mov_b32 v[136:137], v[134:135], v[42:43] op_sel:[1,0]
	v_mov_b32_e32 v135, v43
	v_fmamk_f32 v26, v133, 0xba800000, v26
	v_fmamk_f32 v29, v133, 0xba800000, v29
	v_fmac_f32_e32 v28, 0xba800000, v133
	v_pk_add_f32 v[42:43], v[136:137], v[134:135]
	v_pk_mul_f32 v[134:135], v[28:29], v[28:29]
	v_pk_mul_f32 v[136:137], v[26:27], v[26:27]
	v_fmamk_f32 v22, v133, 0xba800000, v22
	v_pk_mov_b32 v[138:139], v[136:137], v[134:135] op_sel:[1,0]
	v_mov_b32_e32 v137, v135
	v_fmamk_f32 v23, v133, 0xba800000, v23
	v_fmac_f32_e32 v24, 0xba800000, v133
	v_mul_f32_e32 v0, v22, v22
	v_pk_add_f32 v[134:135], v[138:139], v[136:137]
	v_fmamk_f32 v25, v133, 0xba800000, v25
	v_pk_fma_f32 v[136:137], v[22:23], v[22:23], v[0:1] op_sel_hi:[1,1,0]
	v_mul_f32_e32 v0, v24, v24
	v_pk_add_f32 v[42:43], v[42:43], v[42:43] op_sel_hi:[0,1]
	v_pk_add_f32 v[134:135], v[134:135], v[134:135] op_sel_hi:[0,1]
	v_pk_fma_f32 v[138:139], v[24:25], v[24:25], v[0:1] op_sel_hi:[1,1,0]
	v_fmamk_f32 v21, v133, 0xba800000, v21
	v_fmamk_f32 v20, v133, 0xba800000, v20
	v_fmamk_f32 v19, v133, 0xba800000, v19
	v_fmac_f32_e32 v18, 0xba800000, v133
	v_mul_f32_e32 v136, v18, v18
	v_mul_f32_e32 v138, v19, v19
	v_mul_f32_e32 v42, v20, v20
	v_mul_f32_e32 v134, v21, v21
	v_pk_add_f32 v[136:137], v[136:137], v[138:139]
	v_pk_add_f32 v[42:43], v[42:43], v[134:135]
	v_mov_b32_e32 v135, v38
	v_pk_add_f32 v[42:43], v[136:137], v[42:43]
	s_nop 0
	v_mov_b32_e32 v134, v42
	v_mov_b32_e32 v38, v43
	v_pk_add_f32 v[38:39], v[134:135], v[38:39]
	v_mov_b32_e32 v204, v38
	v_mov_b32_e32 v205, v39
	s_nop 1
	v_add_f32_dpp v204, v204, v204 quad_perm:[1,0,3,2] row_mask:0xf bank_mask:0xf
	v_add_f32_dpp v205, v205, v205 quad_perm:[1,0,3,2] row_mask:0xf bank_mask:0xf
	s_nop 1
	v_add_f32_dpp v204, v204, v204 quad_perm:[2,3,0,1] row_mask:0xf bank_mask:0xf
	v_add_f32_dpp v205, v205, v205 quad_perm:[2,3,0,1] row_mask:0xf bank_mask:0xf
	s_nop 1
	v_add_f32_dpp v204, v204, v204 row_ror:4 row_mask:0xf bank_mask:0xf
	v_add_f32_dpp v205, v205, v205 row_ror:4 row_mask:0xf bank_mask:0xf
	s_nop 1
	v_add_f32_dpp v204, v204, v204 row_ror:8 row_mask:0xf bank_mask:0xf
	v_add_f32_dpp v205, v205, v205 row_ror:8 row_mask:0xf bank_mask:0xf
	s_nop 1
	v_add_f32_dpp v204, v204, v204 row_bcast:15 row_mask:0xa bank_mask:0xf
	v_add_f32_dpp v205, v205, v205 row_bcast:15 row_mask:0xa bank_mask:0xf
	s_nop 1
	v_add_f32_dpp v204, v204, v204 row_bcast:31 row_mask:0xc bank_mask:0xf
	v_add_f32_dpp v205, v205, v205 row_bcast:31 row_mask:0xc bank_mask:0xf
	s_nop 1
	v_readlane_b32 s98, v204, 63
	v_readlane_b32 s99, v205, 63
	v_add_u32_e32 v134, s2, v123
	v_ashrrev_i32_e32 v135, 31, v134
	v_lshlrev_b64 v[134:135], 11, v[134:135]
	s_waitcnt lgkmcnt(0)
	s_nop 1
	v_mov_b32_e32 v38, s98
	v_mov_b32_e32 v39, s99
	s_nop 0
	v_pk_fma_f32 v[38:39], v[38:39], s[0:1], v[150:151] op_sel_hi:[1,0,0]
	s_nop 0
	v_mul_f32_e32 v0, 0x4b800000, v39
	v_cmp_gt_f32_e32 vcc, s50, v39
	s_nop 1
	v_cndmask_b32_e32 v0, v39, v0, vcc
	v_rsq_f32_e32 v0, v0
	s_nop 0
	v_mul_f32_e32 v39, 0x45800000, v0
	v_cndmask_b32_e32 v0, v0, v39, vcc
	v_pk_mul_f32 v[42:43], v[120:121], v[0:1] op_sel_hi:[1,0]
	v_pk_mul_f32 v[48:49], v[48:49], v[0:1] op_sel_hi:[1,0]
	v_pk_mul_f32 v[120:121], v[2:3], v[42:43]
	v_pk_mul_f32 v[48:49], v[4:5], v[48:49]
	v_mul_f32_e32 v39, 0xbfb8aa3b, v120
	v_exp_f32_e32 v42, v39
	v_mul_f32_e32 v39, 0xbfb8aa3b, v121
	v_exp_f32_e32 v43, v39
	v_pk_mul_f32 v[46:47], v[46:47], v[0:1] op_sel_hi:[1,0]
	v_pk_mul_f32 v[44:45], v[44:45], v[0:1] op_sel_hi:[1,0]
	v_pk_mul_f32 v[46:47], v[6:7], v[46:47]
	v_pk_add_f32 v[136:137], v[42:43], 1.0 op_sel_hi:[1,0]
	v_lshl_add_u64 v[42:43], v[116:117], 0, v[134:135]
	v_pk_mul_f32 v[44:45], v[8:9], v[44:45]
	v_pk_mul_f32 v[40:41], v[40:41], v[0:1] op_sel_hi:[1,0]
	v_pk_mul_f32 v[34:35], v[34:35], v[0:1] op_sel_hi:[1,0]
	v_mul_f32_e32 v134, 0xbfb8aa3b, v48
	v_mul_f32_e32 v135, 0xbfb8aa3b, v49
	v_exp_f32_e32 v134, v134
	v_exp_f32_e32 v135, v135
	v_rcp_f32_e32 v39, v137
	s_nop 0
	v_mul_f32_e32 v39, v121, v39
	v_pk_add_f32 v[134:135], v[134:135], 1.0 op_sel_hi:[1,0]
	v_rcp_f32_e32 v121, v136
	s_nop 0
	v_mul_f32_e32 v133, v120, v121
	v_pk_mul_f32 v[40:41], v[12:13], v[40:41]
	v_rcp_f32_e32 v120, v135
	s_nop 0
	v_mul_f32_e32 v49, v49, v120
	v_pk_mul_f32 v[34:35], v[14:15], v[34:35]
	v_mul_f32_e32 v120, 0xbfb8aa3b, v46
	v_mul_f32_e32 v121, 0xbfb8aa3b, v47
	v_exp_f32_e32 v120, v120
	v_exp_f32_e32 v121, v121
	v_rcp_f32_e32 v135, v134
	s_nop 0
	v_mul_f32_e32 v134, v48, v135
	v_cvt_pk_bf16_f32 v48, v133, v39
	v_cvt_pk_bf16_f32 v49, v134, v49
	v_pk_add_f32 v[120:121], v[120:121], 1.0 op_sel_hi:[1,0]
	global_store_dwordx2 v[42:43], v[48:49], off
	v_pk_mul_f32 v[36:37], v[36:37], v[0:1] op_sel_hi:[1,0]
	v_mul_f32_e32 v48, 0xbfb8aa3b, v44
	v_mul_f32_e32 v49, 0xbfb8aa3b, v45
	v_exp_f32_e32 v48, v48
	v_exp_f32_e32 v49, v49
	v_rcp_f32_e32 v39, v121
	s_nop 0
	v_mul_f32_e32 v39, v47, v39
	v_pk_add_f32 v[48:49], v[48:49], 1.0 op_sel_hi:[1,0]
	v_rcp_f32_e32 v47, v120
	s_nop 0
	v_mul_f32_e32 v120, v46, v47
	v_pk_mul_f32 v[36:37], v[16:17], v[36:37]
	v_rcp_f32_e32 v46, v49
	s_nop 0
	v_mul_f32_e32 v45, v45, v46
	v_pk_mul_f32 v[46:47], v[118:119], v[0:1] op_sel_hi:[1,0]
	v_rcp_f32_e32 v49, v48
	s_nop 0
	v_mul_f32_e32 v48, v44, v49
	v_pk_mul_f32 v[46:47], v[10:11], v[46:47]
	v_cvt_pk_bf16_f32 v45, v48, v45
	v_mul_f32_e32 v118, 0xbfb8aa3b, v46
	v_mul_f32_e32 v119, 0xbfb8aa3b, v47
	v_exp_f32_e32 v118, v118
	v_exp_f32_e32 v119, v119
	v_cvt_pk_bf16_f32 v44, v120, v39
	global_store_dwordx2 v[42:43], v[44:45], off offset:512
	v_pk_add_f32 v[48:49], v[118:119], 1.0 op_sel_hi:[1,0]
	s_nop 0
	s_nop 0
	v_mul_f32_e32 v45, 0xbfb8aa3b, v41
	v_mul_f32_e32 v44, 0xbfb8aa3b, v40
	v_exp_f32_e32 v44, v44
	v_exp_f32_e32 v45, v45
	v_rcp_f32_e32 v39, v49
	s_nop 0
	v_mul_f32_e32 v39, v47, v39
	v_pk_add_f32 v[44:45], v[44:45], 1.0 op_sel_hi:[1,0]
	v_rcp_f32_e32 v47, v48
	s_nop 0
	v_mul_f32_e32 v48, v46, v47
	v_rcp_f32_e32 v46, v45
	s_nop 0
	v_mul_f32_e32 v41, v41, v46
	v_mul_f32_e32 v46, 0xbfb8aa3b, v34
	v_mul_f32_e32 v47, 0xbfb8aa3b, v35
	v_exp_f32_e32 v46, v46
	v_exp_f32_e32 v47, v47
	v_rcp_f32_e32 v45, v44
	s_nop 0
	v_mul_f32_e32 v44, v40, v45
	v_cvt_pk_bf16_f32 v41, v44, v41
	v_cvt_pk_bf16_f32 v40, v48, v39
	v_pk_add_f32 v[44:45], v[46:47], 1.0 op_sel_hi:[1,0]
	global_store_dwordx2 v[42:43], v[40:41], off offset:1024
	s_nop 0
	v_mul_f32_e32 v40, 0xbfb8aa3b, v36
	v_mul_f32_e32 v41, 0xbfb8aa3b, v37
	v_rcp_f32_e32 v0, v45
	s_nop 0
	v_mul_f32_e32 v0, v35, v0
	v_exp_f32_e32 v40, v40
	v_exp_f32_e32 v41, v41
	s_nop 0
	v_pk_add_f32 v[40:41], v[40:41], 1.0 op_sel_hi:[1,0]
	v_rcp_f32_e32 v35, v44
	s_nop 0
	v_mul_f32_e32 v34, v34, v35
	v_cvt_pk_bf16_f32 v34, v34, v0
	v_rcp_f32_e32 v35, v41
	s_nop 0
	v_mul_f32_e32 v35, v37, v35
	v_rcp_f32_e32 v37, v40
	s_nop 0
	v_mul_f32_e32 v36, v36, v37
	v_mul_f32_e32 v37, 0x4b800000, v38
	v_cmp_gt_f32_e32 vcc, s50, v38
	v_cvt_pk_bf16_f32 v35, v36, v35
	global_store_dwordx2 v[42:43], v[34:35], off offset:1536
	v_cndmask_b32_e32 v37, v38, v37, vcc
	v_rsq_f32_e32 v37, v37
	v_add_u32_e32 v36, s2, v130
	s_add_i32 s2, s2, s97
	v_mul_f32_e32 v0, 0x45800000, v37
	v_cndmask_b32_e32 v0, v37, v0, vcc
	v_pk_mul_f32 v[30:31], v[30:31], v[0:1] op_sel_hi:[1,0]
	v_ashrrev_i32_e32 v37, 31, v36
	v_pk_mul_f32 v[34:35], v[2:3], v[30:31]
	v_lshlrev_b64 v[36:37], 11, v[36:37]
	v_mul_f32_e32 v30, 0xbfb8aa3b, v34
	v_mul_f32_e32 v31, 0xbfb8aa3b, v35
	v_exp_f32_e32 v30, v30
	v_exp_f32_e32 v31, v31
	v_pk_mul_f32 v[32:33], v[32:33], v[0:1] op_sel_hi:[1,0]
	v_pk_mul_f32 v[26:27], v[26:27], v[0:1] op_sel_hi:[1,0]
	v_pk_mul_f32 v[32:33], v[4:5], v[32:33]
	v_pk_add_f32 v[38:39], v[30:31], 1.0 op_sel_hi:[1,0]
	v_lshl_add_u64 v[30:31], v[116:117], 0, v[36:37]
	v_pk_mul_f32 v[26:27], v[6:7], v[26:27]
	v_pk_mul_f32 v[28:29], v[28:29], v[0:1] op_sel_hi:[1,0]
	v_pk_mul_f32 v[22:23], v[22:23], v[0:1] op_sel_hi:[1,0]
	v_rcp_f32_e32 v36, v39
	s_nop 0
	v_mul_f32_e32 v39, v35, v36
	v_mul_f32_e32 v36, 0xbfb8aa3b, v32
	v_mul_f32_e32 v37, 0xbfb8aa3b, v33
	v_exp_f32_e32 v36, v36
	v_exp_f32_e32 v37, v37
	s_nop 0
	v_pk_add_f32 v[36:37], v[36:37], 1.0 op_sel_hi:[1,0]
	v_rcp_f32_e32 v35, v38
	s_nop 0
	v_mul_f32_e32 v38, v34, v35
	v_pk_mul_f32 v[28:29], v[8:9], v[28:29]
	v_rcp_f32_e32 v34, v37
	s_nop 0
	v_mul_f32_e32 v33, v33, v34
	v_pk_mul_f32 v[22:23], v[10:11], v[22:23]
	v_mul_f32_e32 v34, 0xbfb8aa3b, v26
	v_mul_f32_e32 v35, 0xbfb8aa3b, v27
	v_exp_f32_e32 v34, v34
	v_exp_f32_e32 v35, v35
	v_rcp_f32_e32 v37, v36
	s_nop 0
	v_mul_f32_e32 v36, v32, v37
	v_cvt_pk_bf16_f32 v33, v36, v33
	v_cvt_pk_bf16_f32 v32, v38, v39
	v_pk_add_f32 v[34:35], v[34:35], 1.0 op_sel_hi:[1,0]
	global_store_dwordx2 v[30:31], v[32:33], off
	v_pk_mul_f32 v[24:25], v[24:25], v[0:1] op_sel_hi:[1,0]
	v_pk_mul_f32 v[18:19], v[18:19], v[0:1] op_sel_hi:[1,0]
	v_pk_mul_f32 v[24:25], v[12:13], v[24:25]
	v_rcp_f32_e32 v32, v35
	s_nop 0
	v_mul_f32_e32 v35, v27, v32
	v_mul_f32_e32 v32, 0xbfb8aa3b, v28
	v_mul_f32_e32 v33, 0xbfb8aa3b, v29
	v_exp_f32_e32 v32, v32
	v_exp_f32_e32 v33, v33
	s_nop 0
	v_pk_add_f32 v[32:33], v[32:33], 1.0 op_sel_hi:[1,0]
	v_rcp_f32_e32 v27, v34
	s_nop 0
	v_mul_f32_e32 v34, v26, v27
	v_pk_mul_f32 v[18:19], v[14:15], v[18:19]
	v_rcp_f32_e32 v26, v33
	s_nop 0
	v_mul_f32_e32 v29, v29, v26
	v_pk_mul_f32 v[20:21], v[20:21], v[0:1] op_sel_hi:[1,0]
	v_mul_f32_e32 v26, 0xbfb8aa3b, v22
	v_mul_f32_e32 v27, 0xbfb8aa3b, v23
	v_exp_f32_e32 v26, v26
	v_exp_f32_e32 v27, v27
	v_rcp_f32_e32 v33, v32
	s_nop 0
	v_mul_f32_e32 v32, v28, v33
	v_cvt_pk_bf16_f32 v29, v32, v29
	v_cvt_pk_bf16_f32 v28, v34, v35
	v_pk_add_f32 v[26:27], v[26:27], 1.0 op_sel_hi:[1,0]
	global_store_dwordx2 v[30:31], v[28:29], off offset:512
	v_pk_mul_f32 v[20:21], v[16:17], v[20:21]
	v_rcp_f32_e32 v28, v27
	s_nop 0
	v_mul_f32_e32 v27, v23, v28
	v_mul_f32_e32 v28, 0xbfb8aa3b, v24
	v_mul_f32_e32 v29, 0xbfb8aa3b, v25
	v_exp_f32_e32 v28, v28
	v_exp_f32_e32 v29, v29
	s_nop 0
	v_pk_add_f32 v[28:29], v[28:29], 1.0 op_sel_hi:[1,0]
	v_rcp_f32_e32 v23, v26
	s_nop 0
	v_mul_f32_e32 v26, v22, v23
	v_rcp_f32_e32 v22, v29
	s_nop 0
	v_mul_f32_e32 v25, v25, v22
	v_mul_f32_e32 v22, 0xbfb8aa3b, v18
	v_mul_f32_e32 v23, 0xbfb8aa3b, v19
	v_exp_f32_e32 v22, v22
	v_exp_f32_e32 v23, v23
	v_rcp_f32_e32 v29, v28
	s_nop 0
	v_mul_f32_e32 v28, v24, v29
	v_cvt_pk_bf16_f32 v24, v26, v27
	v_cvt_pk_bf16_f32 v25, v28, v25
	v_pk_add_f32 v[22:23], v[22:23], 1.0 op_sel_hi:[1,0]
	global_store_dwordx2 v[30:31], v[24:25], off offset:1024
	s_nop 0
	v_mul_f32_e32 v24, 0xbfb8aa3b, v20
	v_mul_f32_e32 v25, 0xbfb8aa3b, v21
	v_rcp_f32_e32 v0, v23
	s_nop 0
	v_mul_f32_e32 v0, v19, v0
	v_exp_f32_e32 v24, v24
	v_exp_f32_e32 v25, v25
	s_nop 0
	v_pk_add_f32 v[24:25], v[24:25], 1.0 op_sel_hi:[1,0]
	v_rcp_f32_e32 v19, v22
	s_nop 0
	v_mul_f32_e32 v18, v18, v19
	v_cvt_pk_bf16_f32 v18, v18, v0
	v_rcp_f32_e32 v19, v25
	s_nop 0
	v_mul_f32_e32 v19, v21, v19
	v_readlane_b32 s0, v254, 23
	v_rcp_f32_e32 v21, v24
	s_nop 0
	v_mul_f32_e32 v20, v20, v21
	v_cvt_pk_bf16_f32 v19, v20, v19
	s_cmp_ge_i32 s94, s0
	global_store_dwordx2 v[30:31], v[18:19], off offset:1536
	s_barrier
	s_cbranch_scc0 .LBB0_501
	v_readlane_b32 s96, v253, 54
	v_readlane_b32 s18, v253, 51
	v_readlane_b32 s76, v255, 7
	v_readlane_b32 s88, v253, 53
	v_readlane_b32 s97, v253, 55
	v_readlane_b32 s69, v253, 56
	v_readlane_b32 s72, v253, 57
	v_readlane_b32 s74, v253, 59
	s_movk_i32 s71, 0x200
	v_readlane_b32 s75, v253, 60
	v_readlane_b32 s78, v253, 61
	v_readlane_b32 s79, v253, 62
	v_readlane_b32 s80, v253, 63
	v_readlane_b32 s81, v254, 0
	v_readlane_b32 s82, v254, 1
	v_readlane_b32 s83, v254, 2
	s_movk_i32 s85, 0x400
	s_movk_i32 s87, 0x3000
	v_readlane_b32 s89, v254, 3
	v_readlane_b32 s48, v253, 49
	s_movk_i32 s49, 0x3fff
	s_movk_i32 s51, 0x40ff
	s_mov_b32 s52, 0x2aaaaaab
	s_movk_i32 s53, 0x80
	s_movk_i32 s54, 0x7ff
	s_movk_i32 s55, 0xfff
	s_movk_i32 s56, 0x3ff
	s_movk_i32 s57, 0xfa00
	s_movk_i32 s58, 0x1800
	s_movk_i32 s59, 0x500
	s_movk_i32 s60, 0xff00
	s_movk_i32 s61, 0x2ff
	s_movk_i32 s62, 0x1ff
	s_movk_i32 s63, 0x67
	s_movk_i32 s64, 0x6f
	s_movk_i32 s27, 0x77
	s_movk_i32 s29, 0x7f
	v_readlane_b32 s30, v253, 50
	s_mov_b32 s31, 0x3f2aaaab
	s_mov_b32 s43, 0x3f317218
	s_mov_b32 s44, 0x7f800000
	s_mov_b32 s45, 0x33800000
	s_movk_i32 s47, 0x210
	s_movk_i32 s46, 0x1000
	s_mov_b32 s65, 0x16900000
	s_movk_i32 s66, 0x110
	s_movk_i32 s28, 0x2000
	s_mov_b32 s34, 0x2e8ba2e9
	s_movk_i32 s35, 0xea00
	s_movk_i32 s36, 0xd400
	s_movk_i32 s37, 0xaff
	s_mov_b32 s38, 0x7fffea10
	s_mov_b32 s39, 0x7fffea20
	s_mov_b32 s40, 0x7fffea30
	s_mov_b32 s41, 0xffd40000
	s_movk_i32 s42, 0x57f
	v_readlane_b32 s19, v253, 52
	v_readlane_b32 s25, v254, 63
	v_readlane_b32 s26, v255, 9
	v_readlane_b32 s77, v255, 8
	v_readlane_b32 s68, v255, 6
	v_readlane_b32 s73, v253, 58
